# hg_unit_a/c: next-sub-chunk global loads issued back-to-back (removed hipcc's mid-block vmcnt(0)/(5)/(4) waits), bf16->f32 shifts deferred behind one wait after the MFMA sections; P6 EpiC hand-written
# speedup vs baseline: 1.1079x; 1.0196x over previous
; #define LAS __attribute__((address_space(3)))
; __device__ __forceinline__ float bf2f(unsigned u) { return __uint_as_float(u << 16); }
; template <bool FULL>
; __device__ __forceinline__ void hg_load(HgRegs& R, size_t m0, int h, const float* G, const bf16_t* HQ, const bf16_t* HI) {
;     ...
;     for (int i = 0; i < 16; ++i) R.gv[i] = bf2f(((const bf16_t*)G)[base + (size_t)i * 1024]);
; __device__ __forceinline__ void hg_state_update(LAS unsigned char* lds, f32x4 (&S)[8], int w, int r, int g) {
;     const LAS bf16_t* kdT = (const LAS bf16_t*)(lds + HG_KD);
;     const LAS bf16_t* vT = (const LAS bf16_t*)(lds + HG_VT);
;     const LAS float* dl = (const LAS float*)(lds + HG_DL);
;     const bf16x8 b0 = *(const LAS bf16x8*)(vT + (16 * w + r) * 72 + 8 * g), b1 = *(const LAS bf16x8*)(vT + (16 * w + r) * 72 + 32 + 8 * g);
; #pragma unroll
;     for (int i = 0; i < 8; ++i) {
;         const f32x4 d = *(const LAS f32x4*)(dl + 16 * i + 4 * g);
;         S[i] = S[i] * d;
;         const bf16x8 a0 = *(const LAS bf16x8*)(kdT + (16 * i + r) * 72 + 8 * g), a1 = *(const LAS bf16x8*)(kdT + (16 * i + r) * 72 + 32 + 8 * g);
;         S[i] = __builtin_amdgcn_mfma_f32_16x16x32_bf16(a0, b0, S[i], 0, 0, 0);
;         S[i] = __builtin_amdgcn_mfma_f32_16x16x32_bf16(a1, b1, S[i], 0, 0, 0);
;     }
; }
.LBB0_210:
	s_waitcnt lgkmcnt(0)
	s_barrier
	ds_read_b128 v[64:67], v75 offset:34816
	v_add_u32_e32 v63, 0, v73
	v_add_u32_e32 v63, 0x1cc00, v63
	ds_read_b128 v[108:111], v63
	ds_read_b128 v[112:115], v74 offset:53248
	ds_read_b128 v[116:119], v74 offset:53312
	ds_read_b128 v[120:123], v75 offset:34880
	ds_read_b128 v[124:127], v63 offset:64
	s_waitcnt lgkmcnt(4)
	v_pk_mul_f32 v[28:29], v[28:29], v[108:109]
	v_pk_mul_f32 v[30:31], v[30:31], v[110:111]
	ds_read_b128 v[108:111], v75 offset:37184
	s_add_u32 s16, s16, 0x20000
	s_waitcnt lgkmcnt(4)
	v_mfma_f32_16x16x32_bf16 v[28:31], v[64:67], v[112:115], v[28:31]
	ds_read_b128 v[64:67], v75 offset:37120
	s_waitcnt lgkmcnt(2)
	v_pk_mul_f32 v[24:25], v[24:25], v[124:125]
	v_pk_mul_f32 v[26:27], v[26:27], v[126:127]
	v_mfma_f32_16x16x32_bf16 v[28:31], v[120:123], v[116:119], v[28:31]
	s_addc_u32 s17, s17, 0
	v_add_f32_e32 v91, v91, v62
	s_cmp_eq_u32 s16, 0x80000
	s_waitcnt lgkmcnt(0)
	v_mfma_f32_16x16x32_bf16 v[24:27], v[64:67], v[112:115], v[24:27]
	ds_read_b128 v[64:67], v75 offset:39424
	ds_read_b128 v[120:123], v63 offset:128
	s_waitcnt lgkmcnt(0)
	v_pk_mul_f32 v[20:21], v[20:21], v[120:121]
	v_pk_mul_f32 v[22:23], v[22:23], v[122:123]
	v_mfma_f32_16x16x32_bf16 v[24:27], v[108:111], v[116:119], v[24:27]
	ds_read_b128 v[108:111], v75 offset:39488
	ds_read_b128 v[124:127], v63 offset:192
	s_waitcnt lgkmcnt(0)
	v_pk_mul_f32 v[16:17], v[16:17], v[124:125]
	v_mfma_f32_16x16x32_bf16 v[20:23], v[64:67], v[112:115], v[20:23]
	ds_read_b128 v[64:67], v75 offset:41728
	v_pk_mul_f32 v[18:19], v[18:19], v[126:127]
	v_mfma_f32_16x16x32_bf16 v[20:23], v[108:111], v[116:119], v[20:23]
	ds_read_b128 v[108:111], v75 offset:41792
	s_waitcnt lgkmcnt(1)
	v_mfma_f32_16x16x32_bf16 v[16:19], v[64:67], v[112:115], v[16:19]
	ds_read_b128 v[64:67], v75 offset:44032
	ds_read_b128 v[120:123], v63 offset:256
	s_waitcnt lgkmcnt(0)
	v_pk_mul_f32 v[12:13], v[12:13], v[120:121]
	v_pk_mul_f32 v[14:15], v[14:15], v[122:123]
	v_mfma_f32_16x16x32_bf16 v[16:19], v[108:111], v[116:119], v[16:19]
	ds_read_b128 v[108:111], v75 offset:44096
	ds_read_b128 v[124:127], v63 offset:320
	s_waitcnt lgkmcnt(0)
	v_pk_mul_f32 v[8:9], v[8:9], v[124:125]
	v_mfma_f32_16x16x32_bf16 v[12:15], v[64:67], v[112:115], v[12:15]
	ds_read_b128 v[64:67], v75 offset:46336
	v_pk_mul_f32 v[10:11], v[10:11], v[126:127]
	v_mfma_f32_16x16x32_bf16 v[12:15], v[108:111], v[116:119], v[12:15]
	ds_read_b128 v[108:111], v75 offset:46400
	s_waitcnt lgkmcnt(1)
	v_mfma_f32_16x16x32_bf16 v[8:11], v[64:67], v[112:115], v[8:11]
	ds_read_b128 v[64:67], v75 offset:48640
	ds_read_b128 v[120:123], v63 offset:384
	s_waitcnt lgkmcnt(0)
	v_pk_mul_f32 v[0:1], v[0:1], v[120:121]
	v_mfma_f32_16x16x32_bf16 v[8:11], v[108:111], v[116:119], v[8:11]
	ds_read_b128 v[108:111], v75 offset:48704
	ds_read_b128 v[124:127], v63 offset:448
	v_pk_mul_f32 v[2:3], v[2:3], v[122:123]
	s_waitcnt lgkmcnt(0)
	v_pk_mul_f32 v[4:5], v[4:5], v[124:125]
	v_mfma_f32_16x16x32_bf16 v[0:3], v[64:67], v[112:115], v[0:3]
	ds_read_b128 v[64:67], v75 offset:50944
	ds_read_b128 v[120:123], v75 offset:51008
	v_pk_mul_f32 v[6:7], v[6:7], v[126:127]
	v_mfma_f32_16x16x32_bf16 v[0:3], v[108:111], v[116:119], v[0:3]
	s_waitcnt lgkmcnt(1)
	v_mfma_f32_16x16x32_bf16 v[4:7], v[64:67], v[112:115], v[4:7]
	s_waitcnt lgkmcnt(0)
	v_mfma_f32_16x16x32_bf16 v[4:7], v[120:123], v[116:119], v[4:7]
	s_waitcnt vmcnt(16)
	v_lshlrev_b32_e32 v33, 16, v140
	v_lshlrev_b32_e32 v46, 16, v141
	v_lshlrev_b32_e32 v35, 16, v142
	v_lshlrev_b32_e32 v48, 16, v143
	v_lshlrev_b32_e32 v47, 16, v144
	v_lshlrev_b32_e32 v50, 16, v145
	v_lshlrev_b32_e32 v49, 16, v146
	v_lshlrev_b32_e32 v52, 16, v147
	v_lshlrev_b32_e32 v51, 16, v148
	v_lshlrev_b32_e32 v54, 16, v149
	v_lshlrev_b32_e32 v53, 16, v150
	v_lshlrev_b32_e32 v56, 16, v151
	v_lshlrev_b32_e32 v55, 16, v152
	v_lshlrev_b32_e32 v58, 16, v153
	v_lshlrev_b32_e32 v57, 16, v154
	v_lshlrev_b32_e32 v60, 16, v155
	s_cbranch_scc1 .LBB0_225

; __device__ __forceinline__ float bf2f(unsigned u) { return __uint_as_float(u << 16); }
; template <bool FULL>
; __device__ __forceinline__ void hg_load(HgRegs& R, size_t m0, int h, const float* G, const bf16_t* HQ, const bf16_t* HI) {
;     const int tid = threadIdx.x, k = tid & 127, part = tid >> 7;
;     const size_t base = (m0 + 16 * part) * 1024 + h * 128 + k;
; #pragma unroll
;     for (int i = 0; i < 16; ++i) R.gv[i] = bf2f(((const bf16_t*)G)[base + (size_t)i * 1024]);
; #pragma unroll
;     for (int i = 0; i < 16; ++i) R.vv[i] = HI[base + (size_t)i * 1024];
;     if (FULL) {
; #pragma unroll
;         for (int i = 0; i < 16; ++i) R.qv[i] = HQ[base + (size_t)i * 1024];
;     }
; }
.LBB0_221:
	s_or_b64 exec, exec, s[18:19]
	s_cmp_eq_u32 s16, 0x60000
	s_cbranch_scc1 .LBB0_210
	v_lshl_add_u64 v[46:47], v[44:45], 0, s[16:17]
	v_add_co_u32_e32 v48, vcc, 0x20000, v46
	s_nop 1
	v_addc_co_u32_e32 v49, vcc, 0, v47, vcc
	v_add_co_u32_e32 v50, vcc, 0x21000, v46
	s_nop 1
	v_addc_co_u32_e32 v51, vcc, 0, v47, vcc
	v_add_co_u32_e32 v52, vcc, 0x22000, v46
	s_nop 1
	v_addc_co_u32_e32 v53, vcc, 0, v47, vcc
	v_add_co_u32_e32 v54, vcc, 0x23000, v46
	s_nop 1
	v_addc_co_u32_e32 v55, vcc, 0, v47, vcc
	global_load_ushort v141, v[48:49], off offset:2048
	global_load_ushort v143, v[50:51], off offset:2048
	global_load_ushort v145, v[52:53], off offset:2048
	global_load_ushort v147, v[54:55], off offset:2048
	global_load_ushort v146, v[54:55], off
	global_load_ushort v144, v[52:53], off
	global_load_ushort v142, v[50:51], off
	global_load_ushort v140, v[48:49], off
	v_add_co_u32_e32 v48, vcc, 0x24000, v46
	s_nop 0
	s_nop 0
	v_addc_co_u32_e32 v49, vcc, 0, v47, vcc
	v_add_co_u32_e32 v50, vcc, 0x25000, v46
	s_nop 1
	v_addc_co_u32_e32 v51, vcc, 0, v47, vcc
	v_add_co_u32_e32 v52, vcc, 0x26000, v46
	s_nop 1
	v_addc_co_u32_e32 v53, vcc, 0, v47, vcc
	v_add_co_u32_e32 v46, vcc, 0x27000, v46
	s_nop 1
	v_addc_co_u32_e32 v47, vcc, 0, v47, vcc
	global_load_ushort v149, v[48:49], off offset:2048
	global_load_ushort v151, v[50:51], off offset:2048
	global_load_ushort v153, v[52:53], off offset:2048
	global_load_ushort v155, v[46:47], off offset:2048
	global_load_ushort v154, v[46:47], off
	global_load_ushort v152, v[52:53], off
	global_load_ushort v150, v[50:51], off
	global_load_ushort v148, v[48:49], off
	v_lshl_add_u64 v[46:47], v[42:43], 0, s[16:17]
	v_add_co_u32_e32 v48, vcc, 0xbc20000, v46
	s_nop 1
	v_addc_co_u32_e32 v49, vcc, 0, v47, vcc
	v_add_co_u32_e32 v50, vcc, 0xbc21000, v46
	s_nop 1
	v_addc_co_u32_e32 v51, vcc, 0, v47, vcc
	v_add_co_u32_e32 v52, vcc, 0xbc22000, v46
	s_nop 1
	v_addc_co_u32_e32 v53, vcc, 0, v47, vcc
	v_add_co_u32_e32 v54, vcc, 0xbc23000, v46
	s_nop 1
	v_addc_co_u32_e32 v55, vcc, 0, v47, vcc
	global_load_ushort v96, v[48:49], off
	global_load_ushort v97, v[48:49], off offset:2048
	global_load_ushort v92, v[50:51], off
	global_load_ushort v98, v[50:51], off offset:2048
	global_load_ushort v93, v[52:53], off
	global_load_ushort v94, v[52:53], off offset:2048
	global_load_ushort v95, v[54:55], off
	global_load_ushort v99, v[54:55], off offset:2048
	v_add_co_u32_e32 v48, vcc, 0xbc24000, v46
	s_nop 0
	s_nop 0
	v_addc_co_u32_e32 v49, vcc, 0, v47, vcc
	v_add_co_u32_e32 v50, vcc, 0xbc25000, v46
	s_nop 0
	s_nop 0
	v_addc_co_u32_e32 v51, vcc, 0, v47, vcc
	v_add_co_u32_e32 v52, vcc, 0xbc26000, v46
	s_nop 1
	v_addc_co_u32_e32 v53, vcc, 0, v47, vcc
	v_add_co_u32_e32 v46, vcc, 0xbc27000, v46
	s_nop 1
	v_addc_co_u32_e32 v47, vcc, 0, v47, vcc
	global_load_ushort v100, v[48:49], off
	global_load_ushort v101, v[48:49], off offset:2048
	global_load_ushort v102, v[50:51], off
	global_load_ushort v105, v[50:51], off offset:2048
	global_load_ushort v103, v[52:53], off
	global_load_ushort v104, v[52:53], off offset:2048
	global_load_ushort v106, v[46:47], off
	global_load_ushort v107, v[46:47], off offset:2048
	s_nop 0
	s_nop 0
	s_nop 0
	s_nop 0
	s_nop 0
	s_nop 0
	s_nop 0
	s_nop 0
	s_nop 0
	s_nop 0
	s_nop 0
	s_nop 0
	s_nop 0
	s_nop 0
	s_branch .LBB0_210

; #define LAS __attribute__((address_space(3)))
; __device__ __forceinline__ unsigned f2bf(float f) { unsigned u = __float_as_uint(f); return (u + 0x7fffu + ((u >> 16) & 1u)) >> 16; }
; __device__ __forceinline__ void hg_unit_c(LAS unsigned char* lds, int unit, const float* G, bf16_t* HQ, const bf16_t* HI, const float* ST, const float* ng) {
;     ...
;         for (int tt = 0; tt < 2; ++tt) {
;             const int tile = 2 * w + tt, ti = tile >> 2, si = tile & 3;
;             f32x4 a = (f32x4){0.f, 0.f, 0.f, 0.f};
;             if (si <= ti) {
; #pragma unroll
;                 for (int kk = 0; kk < 4; ++kk) {
;                     const bf16x8 af = *(const LAS bf16x8*)(qt + (16 * ti + r) * 136 + 32 * kk + 8 * g);
;                     const bf16x8 bf = *(const LAS bf16x8*)(kt + (16 * si + r) * 136 + 32 * kk + 8 * g);
;                     a = __builtin_amdgcn_mfma_f32_16x16x32_bf16(af, bf, a, 0, 0, 0);
;                 }
;             }
; #pragma unroll
;             for (int rg = 0; rg < 4; ++rg) {
;                 const int t = 16 * ti + 4 * g + rg, s = 16 * si + r;
;                 As[t * 72 + s] = (bf16_t)f2bf((s <= t) ? a[rg] : 0.f);
;             }
;         }
;         __syncthreads();
;         f32x4 o[4];
;         {
;             const bf16x8 vb0 = *(const LAS bf16x8*)(vT + (16 * w + r) * 72 + 8 * g), vb1 = *(const LAS bf16x8*)(vT + (16 * w + r) * 72 + 32 + 8 * g);
;             bf16x8 sb[4];
; #pragma unroll
;             for (int kk = 0; kk < 4; ++kk) sb[kk] = *(const LAS bf16x8*)(SpT + r * 136 + 32 * kk + 8 * g);
; #pragma unroll
;             for (int ti = 0; ti < 4; ++ti) {
;                 f32x4 a = (f32x4){0.f, 0.f, 0.f, 0.f};
;                 const bf16x8 a0 = *(const LAS bf16x8*)(As + (16 * ti + r) * 72 + 8 * g), a1 = *(const LAS bf16x8*)(As + (16 * ti + r) * 72 + 32 + 8 * g);
;                 a = __builtin_amdgcn_mfma_f32_16x16x32_bf16(a0, vb0, a, 0, 0, 0);
;                 a = __builtin_amdgcn_mfma_f32_16x16x32_bf16(a1, vb1, a, 0, 0, 0);
; #pragma unroll
;                 for (int kk = 0; kk < 4; ++kk) {
;                     const bf16x8 qf = *(const LAS bf16x8*)(qt + (16 * ti + r) * 136 + 32 * kk + 8 * g);
;                     a = __builtin_amdgcn_mfma_f32_16x16x32_bf16(qf, sb[kk], a, 0, 0, 0);
;                 }
;                 o[ti] = a;
;             }
;         }
;         hg_state_update(lds, S, w, r, g);
.LBB0_431:
	s_or_b64 exec, exec, s[40:41]
	s_nop 5
	v_cndmask_b32_e64 v32, v32, 0, s[18:19]
	v_bfe_u32 v36, v32, 16, 1
	v_add3_u32 v32, v32, v36, s90
	ds_write_b16_d16_hi v101, v32
	v_cndmask_b32_e64 v32, v33, 0, s[20:21]
	v_bfe_u32 v33, v32, 16, 1
	v_add3_u32 v32, v32, v33, s90
	ds_write_b16_d16_hi v102, v32
	v_cndmask_b32_e64 v32, v34, 0, s[22:23]
	v_bfe_u32 v33, v32, 16, 1
	v_add3_u32 v32, v32, v33, s90
	ds_write_b16_d16_hi v103, v32
	v_cndmask_b32_e64 v32, v35, 0, s[24:25]
	v_bfe_u32 v33, v32, 16, 1
	v_add3_u32 v32, v32, v33, s90
	ds_write_b16_d16_hi v104, v32
	s_waitcnt lgkmcnt(0)
	s_barrier
	ds_read_b128 v[168:171], v97
	ds_read_b128 v[36:39], v90 offset:53248
	ds_read_b128 v[172:175], v97 offset:64
	ds_read_b128 v[32:35], v90 offset:53312
	v_add_u32_e32 v80, v88, v85
	ds_read_b128 v[176:179], v80
	s_waitcnt lgkmcnt(3)
	v_mfma_f32_16x16x32_bf16 v[168:171], v[168:171], v[36:39], 0
	v_add_u32_e32 v81, v87, v86
	ds_read_b128 v[180:183], v81
	s_waitcnt lgkmcnt(2)
	v_mfma_f32_16x16x32_bf16 v[168:171], v[172:175], v[32:35], v[168:171]
	ds_read_b128 v[172:175], v80 offset:64
	ds_read_b128 v[184:187], v81 offset:64
	s_waitcnt lgkmcnt(2)
	v_mfma_f32_16x16x32_bf16 v[168:171], v[176:179], v[180:183], v[168:171]
	ds_read_b128 v[176:179], v80 offset:128
	ds_read_b128 v[188:191], v81 offset:128
	s_waitcnt lgkmcnt(2)
	v_mfma_f32_16x16x32_bf16 v[168:171], v[172:175], v[184:187], v[168:171]
	ds_read_b128 v[172:175], v80 offset:192
	ds_read_b128 v[192:195], v81 offset:192
	ds_read_b128 v[196:199], v129
	ds_read_b128 v[202:205], v129 offset:4352
	s_waitcnt lgkmcnt(4)
	v_mfma_f32_16x16x32_bf16 v[168:171], v[176:179], v[188:191], v[168:171]
	ds_read_b128 v[176:179], v98
	v_add_u32_e32 v80, 0x1cc00, v88
	s_waitcnt lgkmcnt(3)
	v_mfma_f32_16x16x32_bf16 v[168:171], v[172:175], v[192:195], v[168:171]
	ds_read_b128 v[172:175], v98 offset:64
	s_waitcnt lgkmcnt(1)
	v_mfma_f32_16x16x32_bf16 v[176:179], v[176:179], v[36:39], 0
	s_waitcnt lgkmcnt(0)
	v_mfma_f32_16x16x32_bf16 v[172:175], v[172:175], v[32:35], v[176:179]
	s_nop 5
	ds_read_b128 v[176:179], v129 offset:64
	v_mfma_f32_16x16x32_bf16 v[172:175], v[196:199], v[180:183], v[172:175]
	ds_read_b128 v[196:199], v129 offset:128
	s_waitcnt lgkmcnt(1)
	v_mfma_f32_16x16x32_bf16 v[172:175], v[176:179], v[184:187], v[172:175]
	ds_read_b128 v[176:179], v129 offset:192
	s_waitcnt lgkmcnt(1)
	v_mfma_f32_16x16x32_bf16 v[172:175], v[196:199], v[188:191], v[172:175]
	ds_read_b128 v[196:199], v99
	s_waitcnt lgkmcnt(1)
	v_mfma_f32_16x16x32_bf16 v[172:175], v[176:179], v[192:195], v[172:175]
	ds_read_b128 v[176:179], v99 offset:64
	s_waitcnt lgkmcnt(1)
	v_mfma_f32_16x16x32_bf16 v[196:199], v[196:199], v[36:39], 0
	s_waitcnt lgkmcnt(0)
	v_mfma_f32_16x16x32_bf16 v[176:179], v[176:179], v[32:35], v[196:199]
	s_nop 5
	ds_read_b128 v[196:199], v129 offset:4416
	v_mfma_f32_16x16x32_bf16 v[176:179], v[202:205], v[180:183], v[176:179]
	ds_read_b128 v[202:205], v129 offset:4480
	s_waitcnt lgkmcnt(1)
	v_mfma_f32_16x16x32_bf16 v[176:179], v[196:199], v[184:187], v[176:179]
	ds_read_b128 v[196:199], v129 offset:4544
	s_waitcnt lgkmcnt(1)
	v_mfma_f32_16x16x32_bf16 v[176:179], v[202:205], v[188:191], v[176:179]
	ds_read_b128 v[202:205], v100
	ds_read_b128 v[206:209], v100 offset:64
	s_waitcnt lgkmcnt(1)
	v_mfma_f32_16x16x32_bf16 v[202:205], v[202:205], v[36:39], 0
	v_mfma_f32_16x16x32_bf16 v[176:179], v[196:199], v[192:195], v[176:179]
	ds_read_b128 v[196:199], v129 offset:8704
	ds_read_b128 v[210:213], v129 offset:8768
	ds_read_b128 v[214:217], v80
	ds_read_b128 v[218:221], v129 offset:8832
	ds_read_b128 v[222:225], v129 offset:8896
	s_waitcnt lgkmcnt(2)
	v_pk_mul_f32 v[18:19], v[18:19], v[216:217]
	v_mfma_f32_16x16x32_bf16 v[202:205], v[206:209], v[32:35], v[202:205]
	ds_read_b128 v[206:209], v80 offset:64
	v_pk_mul_f32 v[16:17], v[16:17], v[214:215]
	s_waitcnt lgkmcnt(0)
	v_pk_mul_f32 v[26:27], v[26:27], v[208:209]
	v_mfma_f32_16x16x32_bf16 v[180:183], v[196:199], v[180:183], v[202:205]
	ds_read_b128 v[196:199], v91 offset:34816
	s_nop 1
	ds_read_b128 v[202:205], v91 offset:34880
	v_pk_mul_f32 v[24:25], v[24:25], v[206:207]
	v_mfma_f32_16x16x32_bf16 v[180:183], v[210:213], v[184:187], v[180:183]
	ds_read_b128 v[184:187], v80 offset:128
	ds_read_b128 v[206:209], v91 offset:37120
	ds_read_b128 v[210:213], v91 offset:37184
	s_waitcnt lgkmcnt(2)
	v_pk_mul_f32 v[22:23], v[22:23], v[186:187]
	v_mfma_f32_16x16x32_bf16 v[180:183], v[218:221], v[188:191], v[180:183]
	ds_read_b128 v[188:191], v80 offset:192
	v_pk_mul_f32 v[20:21], v[20:21], v[184:185]
	s_waitcnt lgkmcnt(0)
	v_pk_mul_f32 v[30:31], v[30:31], v[190:191]
	v_mfma_f32_16x16x32_bf16 v[16:19], v[196:199], v[36:39], v[16:19]
	v_mul_f32_e64 v28, v28, v188
	v_mul_f32_e64 v29, v29, v189
	v_mfma_f32_16x16x32_bf16 v[24:27], v[206:209], v[36:39], v[24:27]
	v_mfma_f32_16x16x32_bf16 v[180:183], v[222:225], v[192:195], v[180:183]
	ds_read_b128 v[184:187], v91 offset:39424
	ds_read_b128 v[192:195], v91 offset:39488
	ds_read_b128 v[188:191], v91 offset:41728
	ds_read_b128 v[196:199], v91 offset:41792
	ds_read_b128 v[214:217], v91 offset:44032
	ds_read_b128 v[218:221], v91 offset:44096
	v_mfma_f32_16x16x32_bf16 v[16:19], v[202:205], v[32:35], v[16:19]
	ds_read_b128 v[202:205], v80 offset:256
	ds_read_b128 v[222:225], v80 offset:320
	ds_read_b128 v[226:229], v91 offset:46336
	ds_read_b128 v[230:233], v91 offset:46400
	ds_read_b128 v[206:209], v91 offset:48640
	ds_read_b128 v[234:237], v91 offset:48704
	ds_read_b128 v[238:241], v80 offset:384
	ds_read_b128 v[242:245], v80 offset:448
	v_add_u32_e32 v80, 0x1e00, v131
	v_mfma_f32_16x16x32_bf16 v[24:27], v[210:213], v[32:35], v[24:27]
	ds_read_b128 v[210:213], v91 offset:50944
	ds_read_b128 v[246:249], v91 offset:51008
	s_waitcnt lgkmcnt(0)
	s_barrier
; #define LAS __attribute__((address_space(3)))
; __device__ __forceinline__ unsigned cvt_pk_bf16(float lo, float hi) { f32x2_t v = {lo, hi}; bf16x2_t b = __builtin_convertvector(v, bf16x2_t); return __builtin_bit_cast(unsigned, b); }
; __device__ __forceinline__ void hg_unit_c(LAS unsigned char* lds, int unit, const float* G, bf16_t* HQ, const bf16_t* HI, const float* ST, const float* ng) {
;     ...
;         hg_state_update(lds, S, w, r, g);
;         __syncthreads();
; #pragma unroll
;         for (int ti = 0; ti < 4; ++ti)
; #pragma unroll
;             for (int rg = 0; rg < 4; ++rg) Os[(16 * ti + 4 * g + rg) * 132 + 16 * w + r] = o[ti][rg];
;         __syncthreads();
;         {
;             const int t = tid >> 3, sg = tid & 7;
;             f32x4 v[4]; float ss = 0.f;
; #pragma unroll
;             for (int i = 0; i < 4; ++i) { v[i] = *(const LAS f32x4*)(Os + t * 132 + 16 * sg + 4 * i); ss += (v[i][0] * v[i][0] + v[i][1] * v[i][1]) + (v[i][2] * v[i][2] + v[i][3] * v[i][3]); }
;             ss += __shfl_xor(ss, 1); ss += __shfl_xor(ss, 2); ss += __shfl_xor(ss, 4);
;             const float rstd = __builtin_amdgcn_rsqf(ss * (1.f / 128.f) + RMS_EPS);
;             const float* gp = ng + h * 128 + 16 * sg;
;             unsigned pk[8];
; #pragma unroll
;             for (int i = 0; i < 4; ++i) {
;                 const f32x4 gg = *(const f32x4*)(gp + 4 * i);
;                 pk[2 * i] = cvt_pk_bf16(v[i][0] * rstd * gg[0], v[i][1] * rstd * gg[1]);
;                 pk[2 * i + 1] = cvt_pk_bf16(v[i][2] * rstd * gg[2], v[i][3] * rstd * gg[3]);
;             }
;             bf16_t* op = HQ + (m0 + t) * 1024 + h * 128 + 16 * sg;
;             *(u32x4*)op = (u32x4){pk[0], pk[1], pk[2], pk[3]};
;             *(u32x4*)(op + 8) = (u32x4){pk[4], pk[5], pk[6], pk[7]};
;         }
	ds_write_b32 v130, v168
	ds_write2_b32 v131, v169, v170 offset1:132
	ds_write2_b32 v80, v172, v173 offset0:60 offset1:192
	v_add_u32_e32 v80, 0x2200, v131
	ds_write2_b32 v80, v174, v175 offset0:68 offset1:200
	v_add_u32_e32 v80, 0x3f00, v131
	ds_write2_b32 v80, v176, v177 offset0:60 offset1:192
	v_add_u32_e32 v80, 0x4400, v131
	ds_write2_b32 v80, v178, v179 offset0:4 offset1:136
	v_add_u32_e32 v80, 0x6000, v131
	ds_write2_b32 v80, v180, v181 offset0:60 offset1:192
	v_add_u32_e32 v80, 0x6400, v131
	ds_write_b32 v131, v171 offset:1056
	ds_write2_b32 v80, v182, v183 offset0:68 offset1:200
	s_waitcnt lgkmcnt(0)
	s_barrier
	global_load_dwordx4 v[168:171], v[56:57], off
	global_load_dwordx4 v[172:175], v[56:57], off offset:16
	global_load_dwordx4 v[176:179], v[56:57], off offset:32
	global_load_dwordx4 v[180:183], v[56:57], off offset:48
	v_mfma_f32_16x16x32_bf16 v[20:23], v[184:187], v[36:39], v[20:23]
	ds_read_b128 v[184:187], v132
	v_pk_mul_f32 v[0:1], v[0:1], v[202:203]
	v_pk_mul_f32 v[2:3], v[2:3], v[204:205]
	v_mfma_f32_16x16x32_bf16 v[28:31], v[188:191], v[36:39], v[28:31]
	v_mul_f32_e64 v6, v6, v224
	v_mul_f32_e64 v7, v7, v225
	s_waitcnt lgkmcnt(0)
	v_pk_mul_f32 v[80:81], v[186:187], v[186:187]
	v_pk_mul_f32 v[202:203], v[184:185], v[184:185]
	v_mfma_f32_16x16x32_bf16 v[20:23], v[192:195], v[32:35], v[20:23]
	v_pk_mov_b32 v[204:205], v[202:203], v[80:81] op_sel:[1,0]
	v_mov_b32_e32 v203, v81
	v_pk_add_f32 v[80:81], v[204:205], v[202:203]
	v_mfma_f32_16x16x32_bf16 v[28:31], v[196:199], v[32:35], v[28:31]
	ds_read_b128 v[188:191], v132 offset:16
	ds_read_b128 v[192:195], v132 offset:32
	ds_read_b128 v[196:199], v132 offset:48
	v_pk_add_f32 v[80:81], v[80:81], v[80:81] op_sel:[0,1] op_sel_hi:[1,0]
	v_pk_mul_f32 v[4:5], v[4:5], v[222:223]
	s_waitcnt lgkmcnt(2)
	v_pk_mul_f32 v[202:203], v[190:191], v[190:191]
	v_pk_mul_f32 v[204:205], v[188:189], v[188:189]
	v_mfma_f32_16x16x32_bf16 v[0:3], v[214:217], v[36:39], v[0:3]
	v_pk_mov_b32 v[214:215], v[204:205], v[202:203] op_sel:[1,0]
	v_mov_b32_e32 v205, v203
	v_pk_add_f32 v[202:203], v[214:215], v[204:205]
	s_waitcnt lgkmcnt(0)
	v_mul_f32_e32 v167, v196, v196
	v_mul_f32_e32 v201, v197, v197
	v_pk_add_f32 v[202:203], v[202:203], v[202:203] op_sel:[0,1] op_sel_hi:[1,0]
	v_mov_b32_e32 v81, v167
	v_mov_b32_e32 v203, v201
	v_pk_add_f32 v[80:81], v[80:81], v[202:203]
	v_mul_f32_e32 v202, v193, v193
	v_mul_f32_e32 v204, v198, v198
	v_pk_fma_f32 v[202:203], v[192:193], v[192:193], v[202:203] op_sel_hi:[1,1,0]
	v_mul_f32_e32 v214, v199, v199
	v_mov_b32_e32 v203, v204
	v_mul_f32_e32 v204, v195, v195
	v_pk_fma_f32 v[204:205], v[194:195], v[194:195], v[204:205] op_sel_hi:[1,1,0]
	v_pk_mul_f32 v[10:11], v[10:11], v[240:241]
	v_mov_b32_e32 v205, v214
	v_pk_add_f32 v[202:203], v[202:203], v[204:205]
	v_pk_mul_f32 v[8:9], v[8:9], v[238:239]
	v_pk_add_f32 v[80:81], v[80:81], v[202:203]
	v_pk_mul_f32 v[14:15], v[14:15], v[244:245]
	v_add_f32_e32 v80, v80, v81
	ds_bpermute_b32 v81, v92, v80
	v_pk_mul_f32 v[12:13], v[12:13], v[242:243]
	v_mfma_f32_16x16x32_bf16 v[4:7], v[226:229], v[36:39], v[4:7]
	s_waitcnt lgkmcnt(0)
	v_add_f32_e32 v80, v80, v81
	ds_bpermute_b32 v81, v93, v80
	v_mfma_f32_16x16x32_bf16 v[8:11], v[206:209], v[36:39], v[8:11]
	s_waitcnt lgkmcnt(0)
	v_add_f32_e32 v80, v80, v81
	ds_bpermute_b32 v81, v94, v80
	v_mfma_f32_16x16x32_bf16 v[12:15], v[210:213], v[36:39], v[12:15]
	s_waitcnt lgkmcnt(0)
	v_add_f32_e32 v36, v80, v81
	v_fmamk_f32 v36, v36, 0x3c000000, v133
	v_rsq_f32_e32 v80, v36
	v_mfma_f32_16x16x32_bf16 v[0:3], v[218:221], v[32:35], v[0:3]
	v_mul_f32_e64 v36, v190, v80
	v_mul_f32_e64 v37, v191, v80
	v_mfma_f32_16x16x32_bf16 v[4:7], v[230:233], v[32:35], v[4:7]
	v_mul_f32_e64 v38, v194, v80
	v_mul_f32_e64 v39, v195, v80
	s_waitcnt vmcnt(2)
	v_pk_mul_f32 v[36:37], v[174:175], v[36:37]
	v_mfma_f32_16x16x32_bf16 v[8:11], v[234:237], v[32:35], v[8:11]
	s_waitcnt vmcnt(1)
	v_pk_mul_f32 v[38:39], v[178:179], v[38:39]
	v_mfma_f32_16x16x32_bf16 v[12:15], v[246:249], v[32:35], v[12:15]
	v_mul_f32_e64 v32, v184, v80
	v_mul_f32_e64 v33, v185, v80
	v_pk_mul_f32 v[34:35], v[186:187], v[80:81] op_sel_hi:[1,0]
	v_pk_mul_f32 v[32:33], v[168:169], v[32:33]
	v_pk_mul_f32 v[34:35], v[170:171], v[34:35]
	v_cvt_pk_bf16_f32 v32, v32, v33
	v_cvt_pk_bf16_f32 v33, v34, v35
	v_pk_mul_f32 v[34:35], v[188:189], v[80:81] op_sel_hi:[1,0]
	s_nop 0
	v_pk_mul_f32 v[34:35], v[172:173], v[34:35]
	s_nop 0
	v_cvt_pk_bf16_f32 v34, v34, v35
	v_cvt_pk_bf16_f32 v35, v36, v37
	v_pk_mul_f32 v[36:37], v[192:193], v[80:81] op_sel_hi:[1,0]
	s_nop 0
	v_pk_mul_f32 v[36:37], v[176:177], v[36:37]
	s_nop 0
	v_cvt_pk_bf16_f32 v36, v36, v37
	v_cvt_pk_bf16_f32 v37, v38, v39
	v_pk_mul_f32 v[38:39], v[196:197], v[80:81] op_sel_hi:[1,0]
	v_pk_mul_f32 v[80:81], v[198:199], v[80:81] op_sel_hi:[1,0]
	s_waitcnt vmcnt(0)
	v_pk_mul_f32 v[38:39], v[180:181], v[38:39]
	v_pk_mul_f32 v[80:81], v[182:183], v[80:81]
	v_cvt_pk_bf16_f32 v38, v38, v39
	v_cvt_pk_bf16_f32 v39, v80, v81
	v_lshl_add_u64 v[80:81], v[58:59], 0, s[38:39]
	s_add_u32 s38, s38, 0x20000
	v_add_co_u32_e32 v80, vcc, s91, v80
	s_addc_u32 s39, s39, 0
	s_nop 0
	v_addc_co_u32_e32 v81, vcc, 0, v81, vcc
	s_cmp_lg_u32 s38, 0x80000
	global_store_dwordx4 v[80:81], v[32:35], off
	global_store_dwordx4 v[80:81], v[36:39], off offset:16
	v_lshlrev_b32_e32 v43, 16, v43
	v_lshlrev_b32_e32 v76, 16, v76
	v_lshlrev_b32_e32 v78, 16, v78
	v_lshlrev_b32_e32 v80, 16, v64
	v_lshlrev_b32_e32 v64, 16, v45
	v_lshlrev_b32_e32 v45, 16, v66
	v_lshlrev_b32_e32 v66, 16, v47
	v_lshlrev_b32_e32 v47, 16, v68
	v_lshlrev_b32_e32 v68, 16, v67
	v_lshlrev_b32_e32 v67, 16, v72
	v_lshlrev_b32_e32 v72, 16, v71
	v_lshlrev_b32_e32 v71, 16, v65
	v_lshlrev_b32_e32 v65, 16, v70
	v_lshlrev_b32_e32 v70, 16, v69
	v_lshlrev_b32_e32 v69, 16, v74
	v_lshlrev_b32_e32 v74, 16, v73
	v_mov_b32_e32 v73, v80
	s_cbranch_scc0 .LBB0_429

; __device__ __forceinline__ float bf2f(unsigned u) { return __uint_as_float(u << 16); }
; template <bool FULL>
; __device__ __forceinline__ void hg_load(HgRegs& R, size_t m0, int h, const float* G, const bf16_t* HQ, const bf16_t* HI) {
;     const int tid = threadIdx.x, k = tid & 127, part = tid >> 7;
;     const size_t base = (m0 + 16 * part) * 1024 + h * 128 + k;
; #pragma unroll
;     for (int i = 0; i < 16; ++i) R.gv[i] = bf2f(((const bf16_t*)G)[base + (size_t)i * 1024]);
; #pragma unroll
;     for (int i = 0; i < 16; ++i) R.vv[i] = HI[base + (size_t)i * 1024];
;     if (FULL) {
; #pragma unroll
;         for (int i = 0; i < 16; ++i) R.qv[i] = HQ[base + (size_t)i * 1024];
;     }
; }
; __device__ __forceinline__ void hg_unit_c(LAS unsigned char* lds, int unit, const float* G, bf16_t* HQ, const bf16_t* HI, const float* ST, const float* ng) {
;     ...
;     for (int sc = 0; sc < 4; ++sc) {
;         const size_t m0 = (size_t)b * SEQ + c * 256 + sc * 64;
;         __syncthreads();
;         (void)hg_prep<true>(lds, R);
;         if (sc < 3) hg_load<true>(R, m0 + 64, h, G, HQ, HI);
;         __syncthreads();
.LBB0_442:
	s_or_b64 exec, exec, s[40:41]
	s_cmp_eq_u32 s38, 0x60000
	s_cbranch_scc1 .LBB0_444
	v_lshl_add_u64 v[32:33], v[62:63], 0, s[38:39]
	v_add_co_u32_e32 v34, vcc, 0x20000, v32
	s_nop 1
	v_addc_co_u32_e32 v35, vcc, 0, v33, vcc
	v_add_co_u32_e32 v36, vcc, 0x21000, v32
	s_nop 1
	v_addc_co_u32_e32 v37, vcc, 0, v33, vcc
	v_add_co_u32_e32 v38, vcc, 0x22000, v32
	s_nop 1
	v_addc_co_u32_e32 v39, vcc, 0, v33, vcc
	v_add_co_u32_e32 v80, vcc, 0x23000, v32
	s_nop 1
	v_addc_co_u32_e32 v81, vcc, 0, v33, vcc
	global_load_ushort v45, v[34:35], off offset:2048
	global_load_ushort v47, v[36:37], off offset:2048
	global_load_ushort v67, v[38:39], off offset:2048
	global_load_ushort v69, v[80:81], off offset:2048
	global_load_ushort v70, v[80:81], off
	global_load_ushort v68, v[38:39], off
	global_load_ushort v66, v[36:37], off
	global_load_ushort v43, v[34:35], off
	v_add_co_u32_e32 v34, vcc, 0x24000, v32
	s_nop 0
	s_nop 0
	v_addc_co_u32_e32 v35, vcc, 0, v33, vcc
	v_add_co_u32_e32 v36, vcc, 0x25000, v32
	s_nop 1
	v_addc_co_u32_e32 v37, vcc, 0, v33, vcc
	v_add_co_u32_e32 v38, vcc, 0x26000, v32
	s_nop 1
	v_addc_co_u32_e32 v39, vcc, 0, v33, vcc
	v_add_co_u32_e32 v32, vcc, 0x27000, v32
	s_nop 1
	v_addc_co_u32_e32 v33, vcc, 0, v33, vcc
	global_load_ushort v71, v[34:35], off offset:2048
	global_load_ushort v73, v[36:37], off offset:2048
	global_load_ushort v76, v[38:39], off offset:2048
	global_load_ushort v78, v[32:33], off offset:2048
	global_load_ushort v64, v[32:33], off
	global_load_ushort v65, v[38:39], off
	global_load_ushort v74, v[36:37], off
	global_load_ushort v72, v[34:35], off
	v_lshl_add_u64 v[32:33], v[60:61], 0, s[38:39]
	v_add_co_u32_e32 v34, vcc, 0xbc20000, v32
	s_nop 0
	s_nop 0
	v_addc_co_u32_e32 v35, vcc, 0, v33, vcc
	v_add_co_u32_e32 v36, vcc, 0xbc21000, v32
	s_nop 0
	s_nop 0
	v_addc_co_u32_e32 v37, vcc, 0, v33, vcc
	v_add_co_u32_e32 v38, vcc, 0xbc22000, v32
	s_nop 1
	v_addc_co_u32_e32 v39, vcc, 0, v33, vcc
	v_add_co_u32_e32 v80, vcc, 0xbc23000, v32
	s_nop 1
	v_addc_co_u32_e32 v81, vcc, 0, v33, vcc
	global_load_ushort v139, v[34:35], off
	global_load_ushort v140, v[34:35], off offset:2048
	global_load_ushort v135, v[36:37], off
	global_load_ushort v141, v[36:37], off offset:2048
	global_load_ushort v136, v[38:39], off
	global_load_ushort v137, v[38:39], off offset:2048
	global_load_ushort v138, v[80:81], off
	global_load_ushort v142, v[80:81], off offset:2048
	v_add_co_u32_e32 v34, vcc, 0xbc24000, v32
	s_nop 1
	v_addc_co_u32_e32 v35, vcc, 0, v33, vcc
	v_add_co_u32_e32 v36, vcc, 0xbc25000, v32
	s_nop 1
	v_addc_co_u32_e32 v37, vcc, 0, v33, vcc
	v_add_co_u32_e32 v38, vcc, 0xbc26000, v32
	s_nop 1
	v_addc_co_u32_e32 v39, vcc, 0, v33, vcc
	v_add_co_u32_e32 v80, vcc, 0xbc27000, v32
	s_nop 1
	v_addc_co_u32_e32 v81, vcc, 0, v33, vcc
	global_load_ushort v143, v[34:35], off
	global_load_ushort v144, v[34:35], off offset:2048
	global_load_ushort v145, v[36:37], off
	global_load_ushort v147, v[36:37], off offset:2048
	global_load_ushort v146, v[38:39], off
	global_load_ushort v151, v[38:39], off offset:2048
	global_load_ushort v148, v[80:81], off
	global_load_ushort v149, v[80:81], off offset:2048
	v_add_co_u32_e32 v34, vcc, 0x5c20000, v32
	s_nop 1
	v_addc_co_u32_e32 v35, vcc, 0, v33, vcc
	v_add_co_u32_e32 v36, vcc, 0x5c21000, v32
	s_nop 1
	v_addc_co_u32_e32 v37, vcc, 0, v33, vcc
	v_add_co_u32_e32 v38, vcc, 0x5c22000, v32
	s_nop 1
	v_addc_co_u32_e32 v39, vcc, 0, v33, vcc
	v_add_co_u32_e32 v80, vcc, 0x5c23000, v32
	s_nop 1
	v_addc_co_u32_e32 v81, vcc, 0, v33, vcc
	global_load_ushort v150, v[34:35], off
	global_load_ushort v156, v[34:35], off offset:2048
	global_load_ushort v152, v[36:37], off
	global_load_ushort v157, v[36:37], off offset:2048
	global_load_ushort v153, v[38:39], off
	global_load_ushort v154, v[38:39], off offset:2048
	global_load_ushort v155, v[80:81], off
	global_load_ushort v158, v[80:81], off offset:2048
	v_add_co_u32_e32 v34, vcc, 0x5c24000, v32
	s_nop 0
	s_nop 0
	v_addc_co_u32_e32 v35, vcc, 0, v33, vcc
	v_add_co_u32_e32 v36, vcc, 0x5c25000, v32
	s_nop 0
	s_nop 0
	v_addc_co_u32_e32 v37, vcc, 0, v33, vcc
	v_add_co_u32_e32 v38, vcc, 0x5c26000, v32
	s_nop 0
	s_nop 0
	v_addc_co_u32_e32 v39, vcc, 0, v33, vcc
	v_add_co_u32_e32 v32, vcc, 0x5c27000, v32
	s_nop 0
	s_nop 0
	v_addc_co_u32_e32 v33, vcc, 0, v33, vcc
	global_load_ushort v159, v[34:35], off
	global_load_ushort v160, v[34:35], off offset:2048
	global_load_ushort v161, v[36:37], off
	global_load_ushort v164, v[36:37], off offset:2048
	global_load_ushort v162, v[38:39], off
	global_load_ushort v163, v[38:39], off offset:2048
	global_load_ushort v165, v[32:33], off
	global_load_ushort v166, v[32:33], off offset:2048
	s_nop 0
	s_nop 0
	s_nop 0
	s_nop 0
	s_nop 0
	s_nop 0
	s_nop 0
	s_nop 0
	s_nop 0
	s_nop 0

; __device__ __forceinline__ unsigned cvt_pk_bf16(float lo, float hi) { f32x2_t v = {lo, hi}; bf16x2_t b = __builtin_convertvector(v, bf16x2_t); return __builtin_bit_cast(unsigned, b); }
; __device__ __forceinline__ float bf2f(unsigned u) { return __uint_as_float(u << 16); }
;     __device__ __forceinline__ void operator()(const f32x4 (&acc)[2][2][4][2], const pg8::Unit& u, int wr, int wc, int fr, int fq) const {
;         const bool second = u.pm >= 64;
;         const int pm = second ? u.pm - 64 : u.pm, pn = second ? u.pn - 4 : u.pn;
;         const int row0 = pm * 256 + wr * 64 + fr, col0 = pn * 256 + wc * 32 + 8 * fq;
; #pragma unroll
;         for (int ai = 0; ai < 2; ++ai)
; #pragma unroll
;         for (int mh = 0; mh < 2; ++mh) {
;             u32x4 gv[2][2], tv[2][2];
; #pragma unroll
;             for (int mm = 0; mm < 2; ++mm)
; #pragma unroll
;                 for (int bj = 0; bj < 2; ++bj) {
;                     const size_t row = (size_t)(row0 + ai * 128 + (2 * mh + mm) * 16); const int col = col0 + bj * 128;
;                     gv[mm][bj] = *(const u32x4*)(gates + row * 2048 + (second ? 1024 : 0) + col);
;                     if (second) tv[mm][bj] = *(const u32x4*)((const bf16_t*)tmp + row * 1024 + col);
;                 }
; #pragma unroll
;             for (int mm = 0; mm < 2; ++mm)
; #pragma unroll
;                 for (int bj = 0; bj < 2; ++bj) {
;                     const int m = 2 * mh + mm;
;                     const size_t row = (size_t)(row0 + ai * 128 + m * 16); const int col = col0 + bj * 128;
;                     const u32x4 gt = gv[mm][bj];
;                     f32x4 a = acc[ai][bj][m][0], b = acc[ai][bj][m][1];
;                     a[0] *= bf2f(gt.x & 0xffffu); a[1] *= bf2f(gt.x >> 16); a[2] *= bf2f(gt.y & 0xffffu); a[3] *= bf2f(gt.y >> 16);
;                     b[0] *= bf2f(gt.z & 0xffffu); b[1] *= bf2f(gt.z >> 16); b[2] *= bf2f(gt.w & 0xffffu); b[3] *= bf2f(gt.w >> 16);
;                     if (!second) { u32x4 w; w.x = cvt_pk_bf16(a[0], a[1]); w.y = cvt_pk_bf16(a[2], a[3]); w.z = cvt_pk_bf16(b[0], b[1]); w.w = cvt_pk_bf16(b[2], b[3]); *(u32x4*)((bf16_t*)tmp + row * 1024 + col) = w; }
.LBB0_612:
	s_lshl_b32 s3, s4, 8
	s_lshl_b32 s17, s24, 8
	s_add_i32 s5, s3, 0xffffc000
	s_add_i32 s19, s17, 0xfffffc00
	s_cmp_gt_i32 s4, 63
	s_cselect_b64 s[26:27], -1, 0
	s_cselect_b32 s3, s5, s3
	s_cselect_b32 s5, s19, s17
	s_cselect_b32 s17, 0x800, 0
	s_add_u32 s24, s72, s17
	s_addc_u32 s25, s73, 0
	s_mov_b32 s19, 0xffff0000
	v_add_u32_e32 v178, s3, v186
	v_or_b32_e32 v176, s5, v188
	v_lshlrev_b32_e32 v177, 1, v176
	v_lshl_add_u32 v180, v178, 12, v177
	v_lshl_add_u32 v181, v178, 11, v177
	global_load_dwordx4 v[72:75], v180, s[24:25]
	global_load_dwordx4 v[84:87], v180, s[24:25] offset:256
	v_add_u32_e32 v176, 0x10000, v180
	global_load_dwordx4 v[96:99], v176, s[24:25]
	global_load_dwordx4 v[100:103], v176, s[24:25] offset:256
	v_add_u32_e32 v177, 0x20000, v180
	global_load_dwordx4 v[144:147], v177, s[24:25]
	global_load_dwordx4 v[148:151], v177, s[24:25] offset:256
	v_add_u32_e32 v178, 0x30000, v180
	global_load_dwordx4 v[152:155], v178, s[24:25]
	global_load_dwordx4 v[156:159], v178, s[24:25] offset:256
	v_add_u32_e32 v179, 0x80000, v180
	global_load_dwordx4 v[192:195], v179, s[24:25]
	global_load_dwordx4 v[196:199], v179, s[24:25] offset:256
	v_add_u32_e32 v176, 0x90000, v180
	global_load_dwordx4 v[202:205], v176, s[24:25]
	global_load_dwordx4 v[206:209], v176, s[24:25] offset:256
	v_add_u32_e32 v177, 0xa0000, v180
	global_load_dwordx4 v[210:213], v177, s[24:25]
	global_load_dwordx4 v[214:217], v177, s[24:25] offset:256
	v_add_u32_e32 v178, 0xb0000, v180
	global_load_dwordx4 v[218:221], v178, s[24:25]
	global_load_dwordx4 v[222:225], v178, s[24:25] offset:256
	s_and_b64 vcc, exec, s[26:27]
	s_cbranch_vccnz .Lepic_second
	v_readfirstlane_b32 s3, v200
	s_nop 0
	s_lshr_b32 s3, s3, 6
	s_cmp_eq_u32 s3, 0
	s_cbranch_scc1 .Ldry_epicf_real
	s_mov_b64 exec, 0
	s_cmp_eq_u32 s3, 1
	s_cbranch_scc1 .Ldry_epicf_c1
	s_cmp_eq_u32 s3, 2
	s_cbranch_scc1 .Ldry_epicf_c2
	s_cmp_eq_u32 s3, 3
	s_cbranch_scc1 .Ldry_epicf_c3
	s_cmp_eq_u32 s3, 4
	s_cbranch_scc1 .Ldry_epicf_c4
	s_cmp_eq_u32 s3, 5
	s_cbranch_scc1 .Ldry_epicf_c5
	s_cmp_eq_u32 s3, 6
	s_cbranch_scc1 .Ldry_epicf_c6
	s_branch .Ldry_epicf_c7
.Ldry_epicf_real:
	s_mov_b64 exec, -1
	s_waitcnt vmcnt(15)
	v_lshlrev_b32_e32 v176, 16, v72
	v_and_b32_e32 v177, s19, v72
	v_lshlrev_b32_e32 v178, 16, v73
	v_and_b32_e32 v179, s19, v73
	v_lshlrev_b32_e32 v182, 16, v74
	v_and_b32_e32 v183, s19, v74
	v_lshlrev_b32_e32 v184, 16, v75
	v_and_b32_e32 v185, s19, v75
	v_pk_mul_f32 v[140:141], v[140:141], v[176:177]
	v_pk_mul_f32 v[142:143], v[142:143], v[178:179]
	v_pk_mul_f32 v[136:137], v[136:137], v[182:183]
	v_pk_mul_f32 v[138:139], v[138:139], v[184:185]
	v_cvt_pk_bf16_f32 v140, v140, v141
	v_cvt_pk_bf16_f32 v141, v142, v143
	v_cvt_pk_bf16_f32 v142, v136, v137
	v_cvt_pk_bf16_f32 v143, v138, v139
	v_mov_b32_e32 v180, v181
	global_store_dwordx4 v180, v[140:143], s[64:65]
	s_waitcnt vmcnt(15)
	v_lshlrev_b32_e32 v176, 16, v84
	v_and_b32_e32 v177, s19, v84
	v_lshlrev_b32_e32 v178, 16, v85
	v_and_b32_e32 v179, s19, v85
	v_lshlrev_b32_e32 v182, 16, v86
	v_and_b32_e32 v183, s19, v86
	v_lshlrev_b32_e32 v184, 16, v87
	v_and_b32_e32 v185, s19, v87
	v_pk_mul_f32 v[132:133], v[132:133], v[176:177]
	v_pk_mul_f32 v[134:135], v[134:135], v[178:179]
	v_pk_mul_f32 v[128:129], v[128:129], v[182:183]
	v_pk_mul_f32 v[130:131], v[130:131], v[184:185]
	v_cvt_pk_bf16_f32 v132, v132, v133
	v_cvt_pk_bf16_f32 v133, v134, v135
	v_cvt_pk_bf16_f32 v134, v128, v129
	v_cvt_pk_bf16_f32 v135, v130, v131
	global_store_dwordx4 v180, v[132:135], s[64:65] offset:256
	s_cbranch_execz .Ldry_epicf_real
.Ldry_epicf_c1:
	s_waitcnt vmcnt(15)
	v_lshlrev_b32_e32 v176, 16, v96
	v_and_b32_e32 v177, s19, v96
	v_lshlrev_b32_e32 v178, 16, v97
	v_and_b32_e32 v179, s19, v97
	v_lshlrev_b32_e32 v182, 16, v98
	v_and_b32_e32 v183, s19, v98
	v_lshlrev_b32_e32 v184, 16, v99
	v_and_b32_e32 v185, s19, v99
	v_pk_mul_f32 v[124:125], v[124:125], v[176:177]
	v_pk_mul_f32 v[126:127], v[126:127], v[178:179]
	v_pk_mul_f32 v[120:121], v[120:121], v[182:183]
	v_pk_mul_f32 v[122:123], v[122:123], v[184:185]
	v_cvt_pk_bf16_f32 v124, v124, v125
	v_cvt_pk_bf16_f32 v125, v126, v127
	v_cvt_pk_bf16_f32 v126, v120, v121
	v_cvt_pk_bf16_f32 v127, v122, v123
	v_add_u32_e32 v180, 0x8000, v181
	global_store_dwordx4 v180, v[124:127], s[64:65]
	s_waitcnt vmcnt(15)
	v_lshlrev_b32_e32 v176, 16, v100
	v_and_b32_e32 v177, s19, v100
	v_lshlrev_b32_e32 v178, 16, v101
	v_and_b32_e32 v179, s19, v101
	v_lshlrev_b32_e32 v182, 16, v102
	v_and_b32_e32 v183, s19, v102
	v_lshlrev_b32_e32 v184, 16, v103
	v_and_b32_e32 v185, s19, v103
	v_pk_mul_f32 v[116:117], v[116:117], v[176:177]
	v_pk_mul_f32 v[118:119], v[118:119], v[178:179]
	v_pk_mul_f32 v[112:113], v[112:113], v[182:183]
	v_pk_mul_f32 v[114:115], v[114:115], v[184:185]
	v_cvt_pk_bf16_f32 v116, v116, v117
	v_cvt_pk_bf16_f32 v117, v118, v119
	v_cvt_pk_bf16_f32 v118, v112, v113
	v_cvt_pk_bf16_f32 v119, v114, v115
	global_store_dwordx4 v180, v[116:119], s[64:65] offset:256
	s_cbranch_execz .Ldry_epicf_real
; __device__ __forceinline__ unsigned cvt_pk_bf16(float lo, float hi) { f32x2_t v = {lo, hi}; bf16x2_t b = __builtin_convertvector(v, bf16x2_t); return __builtin_bit_cast(unsigned, b); }
; __device__ __forceinline__ float bf2f(unsigned u) { return __uint_as_float(u << 16); }
;     __device__ __forceinline__ void operator()(const f32x4 (&acc)[2][2][4][2], const pg8::Unit& u, int wr, int wc, int fr, int fq) const {
;     ...
; #pragma unroll
;             for (int mm = 0; mm < 2; ++mm)
; #pragma unroll
;                 for (int bj = 0; bj < 2; ++bj) {
;                     const int m = 2 * mh + mm;
;                     const size_t row = (size_t)(row0 + ai * 128 + m * 16); const int col = col0 + bj * 128;
;                     const u32x4 gt = gv[mm][bj];
;                     f32x4 a = acc[ai][bj][m][0], b = acc[ai][bj][m][1];
;                     a[0] *= bf2f(gt.x & 0xffffu); a[1] *= bf2f(gt.x >> 16); a[2] *= bf2f(gt.y & 0xffffu); a[3] *= bf2f(gt.y >> 16);
;                     b[0] *= bf2f(gt.z & 0xffffu); b[1] *= bf2f(gt.z >> 16); b[2] *= bf2f(gt.w & 0xffffu); b[3] *= bf2f(gt.w >> 16);
;                     if (!second) { u32x4 w; w.x = cvt_pk_bf16(a[0], a[1]); w.y = cvt_pk_bf16(a[2], a[3]); w.z = cvt_pk_bf16(b[0], b[1]); w.w = cvt_pk_bf16(b[2], b[3]); *(u32x4*)((bf16_t*)tmp + row * 1024 + col) = w; }
.Ldry_epicf_c2:
	s_waitcnt vmcnt(15)
	v_lshlrev_b32_e32 v176, 16, v144
	v_and_b32_e32 v177, s19, v144
	v_lshlrev_b32_e32 v178, 16, v145
	v_and_b32_e32 v179, s19, v145
	v_lshlrev_b32_e32 v182, 16, v146
	v_and_b32_e32 v183, s19, v146
	v_lshlrev_b32_e32 v184, 16, v147
	v_and_b32_e32 v185, s19, v147
	v_pk_mul_f32 v[108:109], v[108:109], v[176:177]
	v_pk_mul_f32 v[110:111], v[110:111], v[178:179]
	v_pk_mul_f32 v[104:105], v[104:105], v[182:183]
	v_pk_mul_f32 v[106:107], v[106:107], v[184:185]
	v_cvt_pk_bf16_f32 v108, v108, v109
	v_cvt_pk_bf16_f32 v109, v110, v111
	v_cvt_pk_bf16_f32 v110, v104, v105
	v_cvt_pk_bf16_f32 v111, v106, v107
	v_add_u32_e32 v180, 0x10000, v181
	global_store_dwordx4 v180, v[108:111], s[64:65]
	s_waitcnt vmcnt(15)
	v_lshlrev_b32_e32 v176, 16, v148
	v_and_b32_e32 v177, s19, v148
	v_lshlrev_b32_e32 v178, 16, v149
	v_and_b32_e32 v179, s19, v149
	v_lshlrev_b32_e32 v182, 16, v150
	v_and_b32_e32 v183, s19, v150
	v_lshlrev_b32_e32 v184, 16, v151
	v_and_b32_e32 v185, s19, v151
	v_pk_mul_f32 v[92:93], v[92:93], v[176:177]
	v_pk_mul_f32 v[94:95], v[94:95], v[178:179]
	v_pk_mul_f32 v[88:89], v[88:89], v[182:183]
	v_pk_mul_f32 v[90:91], v[90:91], v[184:185]
	v_cvt_pk_bf16_f32 v92, v92, v93
	v_cvt_pk_bf16_f32 v93, v94, v95
	v_cvt_pk_bf16_f32 v94, v88, v89
	v_cvt_pk_bf16_f32 v95, v90, v91
	global_store_dwordx4 v180, v[92:95], s[64:65] offset:256
	s_cbranch_execz .Ldry_epicf_real
.Ldry_epicf_c3:
	s_waitcnt vmcnt(15)
	v_lshlrev_b32_e32 v176, 16, v152
	v_and_b32_e32 v177, s19, v152
	v_lshlrev_b32_e32 v178, 16, v153
	v_and_b32_e32 v179, s19, v153
	v_lshlrev_b32_e32 v182, 16, v154
	v_and_b32_e32 v183, s19, v154
	v_lshlrev_b32_e32 v184, 16, v155
	v_and_b32_e32 v185, s19, v155
	v_pk_mul_f32 v[80:81], v[80:81], v[176:177]
	v_pk_mul_f32 v[82:83], v[82:83], v[178:179]
	v_pk_mul_f32 v[76:77], v[76:77], v[182:183]
	v_pk_mul_f32 v[78:79], v[78:79], v[184:185]
	v_cvt_pk_bf16_f32 v80, v80, v81
	v_cvt_pk_bf16_f32 v81, v82, v83
	v_cvt_pk_bf16_f32 v82, v76, v77
	v_cvt_pk_bf16_f32 v83, v78, v79
	v_add_u32_e32 v180, 0x18000, v181
	global_store_dwordx4 v180, v[80:83], s[64:65]
	s_waitcnt vmcnt(15)
	v_lshlrev_b32_e32 v176, 16, v156
	v_and_b32_e32 v177, s19, v156
	v_lshlrev_b32_e32 v178, 16, v157
	v_and_b32_e32 v179, s19, v157
	v_lshlrev_b32_e32 v182, 16, v158
	v_and_b32_e32 v183, s19, v158
	v_lshlrev_b32_e32 v184, 16, v159
	v_and_b32_e32 v185, s19, v159
	v_pk_mul_f32 v[68:69], v[68:69], v[176:177]
	v_pk_mul_f32 v[70:71], v[70:71], v[178:179]
	v_pk_mul_f32 v[64:65], v[64:65], v[182:183]
	v_pk_mul_f32 v[66:67], v[66:67], v[184:185]
	v_cvt_pk_bf16_f32 v68, v68, v69
	v_cvt_pk_bf16_f32 v69, v70, v71
	v_cvt_pk_bf16_f32 v70, v64, v65
	v_cvt_pk_bf16_f32 v71, v66, v67
	global_store_dwordx4 v180, v[68:71], s[64:65] offset:256
	s_cbranch_execz .Ldry_epicf_real
.Ldry_epicf_c4:
	s_waitcnt vmcnt(15)
	v_lshlrev_b32_e32 v176, 16, v192
	v_and_b32_e32 v177, s19, v192
	v_lshlrev_b32_e32 v178, 16, v193
	v_and_b32_e32 v179, s19, v193
	v_lshlrev_b32_e32 v182, 16, v194
	v_and_b32_e32 v183, s19, v194
	v_lshlrev_b32_e32 v184, 16, v195
	v_and_b32_e32 v185, s19, v195
	v_pk_mul_f32 v[60:61], v[60:61], v[176:177]
	v_pk_mul_f32 v[62:63], v[62:63], v[178:179]
	v_pk_mul_f32 v[56:57], v[56:57], v[182:183]
	v_pk_mul_f32 v[58:59], v[58:59], v[184:185]
	v_cvt_pk_bf16_f32 v60, v60, v61
	v_cvt_pk_bf16_f32 v61, v62, v63
	v_cvt_pk_bf16_f32 v62, v56, v57
	v_cvt_pk_bf16_f32 v63, v58, v59
	v_add_u32_e32 v180, 0x40000, v181
	global_store_dwordx4 v180, v[60:63], s[64:65]
	s_waitcnt vmcnt(15)
	v_lshlrev_b32_e32 v176, 16, v196
	v_and_b32_e32 v177, s19, v196
	v_lshlrev_b32_e32 v178, 16, v197
	v_and_b32_e32 v179, s19, v197
	v_lshlrev_b32_e32 v182, 16, v198
	v_and_b32_e32 v183, s19, v198
	v_lshlrev_b32_e32 v184, 16, v199
	v_and_b32_e32 v185, s19, v199
	v_pk_mul_f32 v[52:53], v[52:53], v[176:177]
	v_pk_mul_f32 v[54:55], v[54:55], v[178:179]
	v_pk_mul_f32 v[48:49], v[48:49], v[182:183]
	v_pk_mul_f32 v[50:51], v[50:51], v[184:185]
	v_cvt_pk_bf16_f32 v52, v52, v53
	v_cvt_pk_bf16_f32 v53, v54, v55
	v_cvt_pk_bf16_f32 v54, v48, v49
	v_cvt_pk_bf16_f32 v55, v50, v51
	global_store_dwordx4 v180, v[52:55], s[64:65] offset:256
	s_cbranch_execz .Ldry_epicf_real
.Ldry_epicf_c5:
	s_waitcnt vmcnt(15)
	v_lshlrev_b32_e32 v176, 16, v202
	v_and_b32_e32 v177, s19, v202
	v_lshlrev_b32_e32 v178, 16, v203
	v_and_b32_e32 v179, s19, v203
	v_lshlrev_b32_e32 v182, 16, v204
	v_and_b32_e32 v183, s19, v204
	v_lshlrev_b32_e32 v184, 16, v205
	v_and_b32_e32 v185, s19, v205
	v_pk_mul_f32 v[44:45], v[44:45], v[176:177]
	v_pk_mul_f32 v[46:47], v[46:47], v[178:179]
	v_pk_mul_f32 v[40:41], v[40:41], v[182:183]
	v_pk_mul_f32 v[42:43], v[42:43], v[184:185]
	v_cvt_pk_bf16_f32 v44, v44, v45
	v_cvt_pk_bf16_f32 v45, v46, v47
	v_cvt_pk_bf16_f32 v46, v40, v41
	v_cvt_pk_bf16_f32 v47, v42, v43
	v_add_u32_e32 v180, 0x48000, v181
	global_store_dwordx4 v180, v[44:47], s[64:65]
	s_waitcnt vmcnt(15)
	v_lshlrev_b32_e32 v176, 16, v206
	v_and_b32_e32 v177, s19, v206
	v_lshlrev_b32_e32 v178, 16, v207
	v_and_b32_e32 v179, s19, v207
	v_lshlrev_b32_e32 v182, 16, v208
	v_and_b32_e32 v183, s19, v208
	v_lshlrev_b32_e32 v184, 16, v209
	v_and_b32_e32 v185, s19, v209
	v_pk_mul_f32 v[36:37], v[36:37], v[176:177]
	v_pk_mul_f32 v[38:39], v[38:39], v[178:179]
	v_pk_mul_f32 v[32:33], v[32:33], v[182:183]
	v_pk_mul_f32 v[34:35], v[34:35], v[184:185]
	v_cvt_pk_bf16_f32 v36, v36, v37
	v_cvt_pk_bf16_f32 v37, v38, v39
	v_cvt_pk_bf16_f32 v38, v32, v33
	v_cvt_pk_bf16_f32 v39, v34, v35
	global_store_dwordx4 v180, v[36:39], s[64:65] offset:256
	s_cbranch_execz .Ldry_epicf_real
; __device__ __forceinline__ unsigned cvt_pk_bf16(float lo, float hi) { f32x2_t v = {lo, hi}; bf16x2_t b = __builtin_convertvector(v, bf16x2_t); return __builtin_bit_cast(unsigned, b); }
; __device__ __forceinline__ float bf2f(unsigned u) { return __uint_as_float(u << 16); }
;     __device__ __forceinline__ void operator()(const f32x4 (&acc)[2][2][4][2], const pg8::Unit& u, int wr, int wc, int fr, int fq) const {
;     ...
; #pragma unroll
;             for (int mm = 0; mm < 2; ++mm)
; #pragma unroll
;                 for (int bj = 0; bj < 2; ++bj) {
;                     const int m = 2 * mh + mm;
;                     const size_t row = (size_t)(row0 + ai * 128 + m * 16); const int col = col0 + bj * 128;
;                     const u32x4 gt = gv[mm][bj];
;                     f32x4 a = acc[ai][bj][m][0], b = acc[ai][bj][m][1];
;                     a[0] *= bf2f(gt.x & 0xffffu); a[1] *= bf2f(gt.x >> 16); a[2] *= bf2f(gt.y & 0xffffu); a[3] *= bf2f(gt.y >> 16);
;                     b[0] *= bf2f(gt.z & 0xffffu); b[1] *= bf2f(gt.z >> 16); b[2] *= bf2f(gt.w & 0xffffu); b[3] *= bf2f(gt.w >> 16);
;                     if (!second) { u32x4 w; w.x = cvt_pk_bf16(a[0], a[1]); w.y = cvt_pk_bf16(a[2], a[3]); w.z = cvt_pk_bf16(b[0], b[1]); w.w = cvt_pk_bf16(b[2], b[3]); *(u32x4*)((bf16_t*)tmp + row * 1024 + col) = w; }
;                     else {
;                         { const u32x4 t = tv[mm][bj]; a[0] += bf2f(t.x & 0xffffu); a[1] += bf2f(t.x >> 16); a[2] += bf2f(t.y & 0xffffu); a[3] += bf2f(t.y >> 16);
;                           b[0] += bf2f(t.z & 0xffffu); b[1] += bf2f(t.z >> 16); b[2] += bf2f(t.w & 0xffffu); b[3] += bf2f(t.w >> 16); }
;                         u32x4 w; w.x = cvt_pk_bf16(a[0], a[1]); w.y = cvt_pk_bf16(a[2], a[3]); w.z = cvt_pk_bf16(b[0], b[1]); w.w = cvt_pk_bf16(b[2], b[3]);
;                         *(u32x4*)(Y + row * 1024 + col) = w;
;                     }
.Ldry_epicf_c6:
	s_waitcnt vmcnt(15)
	v_lshlrev_b32_e32 v176, 16, v210
	v_and_b32_e32 v177, s19, v210
	v_lshlrev_b32_e32 v178, 16, v211
	v_and_b32_e32 v179, s19, v211
	v_lshlrev_b32_e32 v182, 16, v212
	v_and_b32_e32 v183, s19, v212
	v_lshlrev_b32_e32 v184, 16, v213
	v_and_b32_e32 v185, s19, v213
	v_pk_mul_f32 v[28:29], v[28:29], v[176:177]
	v_pk_mul_f32 v[30:31], v[30:31], v[178:179]
	v_pk_mul_f32 v[24:25], v[24:25], v[182:183]
	v_pk_mul_f32 v[26:27], v[26:27], v[184:185]
	v_cvt_pk_bf16_f32 v28, v28, v29
	v_cvt_pk_bf16_f32 v29, v30, v31
	v_cvt_pk_bf16_f32 v30, v24, v25
	v_cvt_pk_bf16_f32 v31, v26, v27
	v_add_u32_e32 v180, 0x50000, v181
	global_store_dwordx4 v180, v[28:31], s[64:65]
	s_waitcnt vmcnt(15)
	v_lshlrev_b32_e32 v176, 16, v214
	v_and_b32_e32 v177, s19, v214
	v_lshlrev_b32_e32 v178, 16, v215
	v_and_b32_e32 v179, s19, v215
	v_lshlrev_b32_e32 v182, 16, v216
	v_and_b32_e32 v183, s19, v216
	v_lshlrev_b32_e32 v184, 16, v217
	v_and_b32_e32 v185, s19, v217
	v_pk_mul_f32 v[20:21], v[20:21], v[176:177]
	v_pk_mul_f32 v[22:23], v[22:23], v[178:179]
	v_pk_mul_f32 v[16:17], v[16:17], v[182:183]
	v_pk_mul_f32 v[18:19], v[18:19], v[184:185]
	v_cvt_pk_bf16_f32 v20, v20, v21
	v_cvt_pk_bf16_f32 v21, v22, v23
	v_cvt_pk_bf16_f32 v22, v16, v17
	v_cvt_pk_bf16_f32 v23, v18, v19
	global_store_dwordx4 v180, v[20:23], s[64:65] offset:256
	s_cbranch_execz .Ldry_epicf_real
.Ldry_epicf_c7:
	s_waitcnt vmcnt(15)
	v_lshlrev_b32_e32 v176, 16, v218
	v_and_b32_e32 v177, s19, v218
	v_lshlrev_b32_e32 v178, 16, v219
	v_and_b32_e32 v179, s19, v219
	v_lshlrev_b32_e32 v182, 16, v220
	v_and_b32_e32 v183, s19, v220
	v_lshlrev_b32_e32 v184, 16, v221
	v_and_b32_e32 v185, s19, v221
	v_pk_mul_f32 v[12:13], v[12:13], v[176:177]
	v_pk_mul_f32 v[14:15], v[14:15], v[178:179]
	v_pk_mul_f32 v[8:9], v[8:9], v[182:183]
	v_pk_mul_f32 v[10:11], v[10:11], v[184:185]
	v_cvt_pk_bf16_f32 v12, v12, v13
	v_cvt_pk_bf16_f32 v13, v14, v15
	v_cvt_pk_bf16_f32 v14, v8, v9
	v_cvt_pk_bf16_f32 v15, v10, v11
	v_add_u32_e32 v180, 0x58000, v181
	global_store_dwordx4 v180, v[12:15], s[64:65]
	s_waitcnt vmcnt(15)
	v_lshlrev_b32_e32 v176, 16, v222
	v_and_b32_e32 v177, s19, v222
	v_lshlrev_b32_e32 v178, 16, v223
	v_and_b32_e32 v179, s19, v223
	v_lshlrev_b32_e32 v182, 16, v224
	v_and_b32_e32 v183, s19, v224
	v_lshlrev_b32_e32 v184, 16, v225
	v_and_b32_e32 v185, s19, v225
	v_pk_mul_f32 v[4:5], v[4:5], v[176:177]
	v_pk_mul_f32 v[6:7], v[6:7], v[178:179]
	v_pk_mul_f32 v[0:1], v[0:1], v[182:183]
	v_pk_mul_f32 v[2:3], v[2:3], v[184:185]
	v_cvt_pk_bf16_f32 v4, v4, v5
	v_cvt_pk_bf16_f32 v5, v6, v7
	v_cvt_pk_bf16_f32 v6, v0, v1
	v_cvt_pk_bf16_f32 v7, v2, v3
	global_store_dwordx4 v180, v[4:7], s[64:65] offset:256
	s_cbranch_execz .Ldry_epicf_real
	s_branch .Lepic_done
.Lepic_second:
	v_readfirstlane_b32 s3, v200
	s_nop 0
	s_lshr_b32 s3, s3, 6
	s_cmp_eq_u32 s3, 0
	s_cbranch_scc1 .Ldry_epics_real
	s_mov_b64 exec, 0
	s_cmp_eq_u32 s3, 1
	s_cbranch_scc1 .Ldry_epics_c1
	s_cmp_eq_u32 s3, 2
	s_cbranch_scc1 .Ldry_epics_c2
	s_cmp_eq_u32 s3, 3
	s_cbranch_scc1 .Ldry_epics_c3
	s_cmp_eq_u32 s3, 4
	s_cbranch_scc1 .Ldry_epics_c4
	s_cmp_eq_u32 s3, 5
	s_cbranch_scc1 .Ldry_epics_c5
	s_cmp_eq_u32 s3, 6
	s_cbranch_scc1 .Ldry_epics_c6
	s_branch .Ldry_epics_c7
.Ldry_epics_real:
	s_mov_b64 exec, -1
	s_waitcnt vmcnt(15)
	v_lshlrev_b32_e32 v176, 16, v72
	v_and_b32_e32 v177, s19, v72
	v_lshlrev_b32_e32 v178, 16, v73
	v_and_b32_e32 v179, s19, v73
	v_lshlrev_b32_e32 v182, 16, v74
	v_and_b32_e32 v183, s19, v74
	v_lshlrev_b32_e32 v184, 16, v75
	v_and_b32_e32 v185, s19, v75
	v_pk_mul_f32 v[140:141], v[140:141], v[176:177]
	v_pk_mul_f32 v[142:143], v[142:143], v[178:179]
	v_pk_mul_f32 v[136:137], v[136:137], v[182:183]
	v_pk_mul_f32 v[138:139], v[138:139], v[184:185]
	v_mov_b32_e32 v180, v181
	global_load_dwordx4 v[72:75], v180, s[64:65]
	s_waitcnt vmcnt(15)
	v_lshlrev_b32_e32 v176, 16, v84
	v_and_b32_e32 v177, s19, v84
	v_lshlrev_b32_e32 v178, 16, v85
	v_and_b32_e32 v179, s19, v85
	v_lshlrev_b32_e32 v182, 16, v86
	v_and_b32_e32 v183, s19, v86
	v_lshlrev_b32_e32 v184, 16, v87
	v_and_b32_e32 v185, s19, v87
	v_pk_mul_f32 v[132:133], v[132:133], v[176:177]
	v_pk_mul_f32 v[134:135], v[134:135], v[178:179]
	v_pk_mul_f32 v[128:129], v[128:129], v[182:183]
	v_pk_mul_f32 v[130:131], v[130:131], v[184:185]
	global_load_dwordx4 v[84:87], v180, s[64:65] offset:256
	s_waitcnt vmcnt(15)
	v_lshlrev_b32_e32 v176, 16, v96
	v_and_b32_e32 v177, s19, v96
	v_lshlrev_b32_e32 v178, 16, v97
	v_and_b32_e32 v179, s19, v97
	v_lshlrev_b32_e32 v182, 16, v98
	v_and_b32_e32 v183, s19, v98
	v_lshlrev_b32_e32 v184, 16, v99
	v_and_b32_e32 v185, s19, v99
	v_pk_mul_f32 v[124:125], v[124:125], v[176:177]
	v_pk_mul_f32 v[126:127], v[126:127], v[178:179]
	v_pk_mul_f32 v[120:121], v[120:121], v[182:183]
	v_pk_mul_f32 v[122:123], v[122:123], v[184:185]
	v_add_u32_e32 v180, 0x8000, v181
	global_load_dwordx4 v[96:99], v180, s[64:65]
	s_waitcnt vmcnt(15)
	v_lshlrev_b32_e32 v176, 16, v100
	v_and_b32_e32 v177, s19, v100
	v_lshlrev_b32_e32 v178, 16, v101
	v_and_b32_e32 v179, s19, v101
	v_lshlrev_b32_e32 v182, 16, v102
	v_and_b32_e32 v183, s19, v102
	v_lshlrev_b32_e32 v184, 16, v103
	v_and_b32_e32 v185, s19, v103
	v_pk_mul_f32 v[116:117], v[116:117], v[176:177]
	v_pk_mul_f32 v[118:119], v[118:119], v[178:179]
	v_pk_mul_f32 v[112:113], v[112:113], v[182:183]
	v_pk_mul_f32 v[114:115], v[114:115], v[184:185]
	global_load_dwordx4 v[100:103], v180, s[64:65] offset:256
	s_waitcnt vmcnt(15)
	v_lshlrev_b32_e32 v176, 16, v144
	v_and_b32_e32 v177, s19, v144
	v_lshlrev_b32_e32 v178, 16, v145
	v_and_b32_e32 v179, s19, v145
	v_lshlrev_b32_e32 v182, 16, v146
	v_and_b32_e32 v183, s19, v146
	v_lshlrev_b32_e32 v184, 16, v147
	s_cbranch_execz .Ldry_epics_real
; __device__ __forceinline__ float bf2f(unsigned u) { return __uint_as_float(u << 16); }
;     __device__ __forceinline__ void operator()(const f32x4 (&acc)[2][2][4][2], const pg8::Unit& u, int wr, int wc, int fr, int fq) const {
;     ...
; #pragma unroll
;             for (int mm = 0; mm < 2; ++mm)
; #pragma unroll
;                 for (int bj = 0; bj < 2; ++bj) {
;                     const int m = 2 * mh + mm;
;                     const size_t row = (size_t)(row0 + ai * 128 + m * 16); const int col = col0 + bj * 128;
;                     const u32x4 gt = gv[mm][bj];
;                     f32x4 a = acc[ai][bj][m][0], b = acc[ai][bj][m][1];
;                     a[0] *= bf2f(gt.x & 0xffffu); a[1] *= bf2f(gt.x >> 16); a[2] *= bf2f(gt.y & 0xffffu); a[3] *= bf2f(gt.y >> 16);
;                     b[0] *= bf2f(gt.z & 0xffffu); b[1] *= bf2f(gt.z >> 16); b[2] *= bf2f(gt.w & 0xffffu); b[3] *= bf2f(gt.w >> 16);
.Ldry_epics_c1:
	v_and_b32_e32 v185, s19, v147
	v_pk_mul_f32 v[108:109], v[108:109], v[176:177]
	v_pk_mul_f32 v[110:111], v[110:111], v[178:179]
	v_pk_mul_f32 v[104:105], v[104:105], v[182:183]
	v_pk_mul_f32 v[106:107], v[106:107], v[184:185]
	v_add_u32_e32 v180, 0x10000, v181
	global_load_dwordx4 v[144:147], v180, s[64:65]
	s_waitcnt vmcnt(15)
	v_lshlrev_b32_e32 v176, 16, v148
	v_and_b32_e32 v177, s19, v148
	v_lshlrev_b32_e32 v178, 16, v149
	v_and_b32_e32 v179, s19, v149
	v_lshlrev_b32_e32 v182, 16, v150
	v_and_b32_e32 v183, s19, v150
	v_lshlrev_b32_e32 v184, 16, v151
	v_and_b32_e32 v185, s19, v151
	v_pk_mul_f32 v[92:93], v[92:93], v[176:177]
	v_pk_mul_f32 v[94:95], v[94:95], v[178:179]
	v_pk_mul_f32 v[88:89], v[88:89], v[182:183]
	v_pk_mul_f32 v[90:91], v[90:91], v[184:185]
	global_load_dwordx4 v[148:151], v180, s[64:65] offset:256
	s_waitcnt vmcnt(15)
	v_lshlrev_b32_e32 v176, 16, v152
	v_and_b32_e32 v177, s19, v152
	v_lshlrev_b32_e32 v178, 16, v153
	v_and_b32_e32 v179, s19, v153
	v_lshlrev_b32_e32 v182, 16, v154
	v_and_b32_e32 v183, s19, v154
	v_lshlrev_b32_e32 v184, 16, v155
	v_and_b32_e32 v185, s19, v155
	v_pk_mul_f32 v[80:81], v[80:81], v[176:177]
	v_pk_mul_f32 v[82:83], v[82:83], v[178:179]
	v_pk_mul_f32 v[76:77], v[76:77], v[182:183]
	v_pk_mul_f32 v[78:79], v[78:79], v[184:185]
	v_add_u32_e32 v180, 0x18000, v181
	global_load_dwordx4 v[152:155], v180, s[64:65]
	s_waitcnt vmcnt(15)
	v_lshlrev_b32_e32 v176, 16, v156
	v_and_b32_e32 v177, s19, v156
	v_lshlrev_b32_e32 v178, 16, v157
	v_and_b32_e32 v179, s19, v157
	v_lshlrev_b32_e32 v182, 16, v158
	v_and_b32_e32 v183, s19, v158
	v_lshlrev_b32_e32 v184, 16, v159
	v_and_b32_e32 v185, s19, v159
	v_pk_mul_f32 v[68:69], v[68:69], v[176:177]
	v_pk_mul_f32 v[70:71], v[70:71], v[178:179]
	v_pk_mul_f32 v[64:65], v[64:65], v[182:183]
	v_pk_mul_f32 v[66:67], v[66:67], v[184:185]
	global_load_dwordx4 v[156:159], v180, s[64:65] offset:256
	s_waitcnt vmcnt(15)
	v_lshlrev_b32_e32 v176, 16, v192
	v_and_b32_e32 v177, s19, v192
	v_lshlrev_b32_e32 v178, 16, v193
	v_and_b32_e32 v179, s19, v193
	v_lshlrev_b32_e32 v182, 16, v194
	v_and_b32_e32 v183, s19, v194
	v_lshlrev_b32_e32 v184, 16, v195
	v_and_b32_e32 v185, s19, v195
	v_pk_mul_f32 v[60:61], v[60:61], v[176:177]
	v_pk_mul_f32 v[62:63], v[62:63], v[178:179]
	v_pk_mul_f32 v[56:57], v[56:57], v[182:183]
	v_pk_mul_f32 v[58:59], v[58:59], v[184:185]
	v_add_u32_e32 v180, 0x40000, v181
	global_load_dwordx4 v[192:195], v180, s[64:65]
	s_waitcnt vmcnt(15)
	s_cbranch_execz .Ldry_epics_real
.Ldry_epics_c2:
	v_lshlrev_b32_e32 v176, 16, v196
	v_and_b32_e32 v177, s19, v196
	v_lshlrev_b32_e32 v178, 16, v197
	v_and_b32_e32 v179, s19, v197
	v_lshlrev_b32_e32 v182, 16, v198
	v_and_b32_e32 v183, s19, v198
	v_lshlrev_b32_e32 v184, 16, v199
	v_and_b32_e32 v185, s19, v199
	v_pk_mul_f32 v[52:53], v[52:53], v[176:177]
	v_pk_mul_f32 v[54:55], v[54:55], v[178:179]
	v_pk_mul_f32 v[48:49], v[48:49], v[182:183]
	v_pk_mul_f32 v[50:51], v[50:51], v[184:185]
	global_load_dwordx4 v[196:199], v180, s[64:65] offset:256
	s_waitcnt vmcnt(15)
	v_lshlrev_b32_e32 v176, 16, v202
	v_and_b32_e32 v177, s19, v202
	v_lshlrev_b32_e32 v178, 16, v203
	v_and_b32_e32 v179, s19, v203
	v_lshlrev_b32_e32 v182, 16, v204
	v_and_b32_e32 v183, s19, v204
	v_lshlrev_b32_e32 v184, 16, v205
	v_and_b32_e32 v185, s19, v205
	v_pk_mul_f32 v[44:45], v[44:45], v[176:177]
	v_pk_mul_f32 v[46:47], v[46:47], v[178:179]
	v_pk_mul_f32 v[40:41], v[40:41], v[182:183]
	v_pk_mul_f32 v[42:43], v[42:43], v[184:185]
	v_add_u32_e32 v180, 0x48000, v181
	global_load_dwordx4 v[202:205], v180, s[64:65]
	s_waitcnt vmcnt(15)
	v_lshlrev_b32_e32 v176, 16, v206
	v_and_b32_e32 v177, s19, v206
	v_lshlrev_b32_e32 v178, 16, v207
	v_and_b32_e32 v179, s19, v207
	v_lshlrev_b32_e32 v182, 16, v208
	v_and_b32_e32 v183, s19, v208
	v_lshlrev_b32_e32 v184, 16, v209
	v_and_b32_e32 v185, s19, v209
	v_pk_mul_f32 v[36:37], v[36:37], v[176:177]
	v_pk_mul_f32 v[38:39], v[38:39], v[178:179]
	v_pk_mul_f32 v[32:33], v[32:33], v[182:183]
	v_pk_mul_f32 v[34:35], v[34:35], v[184:185]
	global_load_dwordx4 v[206:209], v180, s[64:65] offset:256
	s_waitcnt vmcnt(15)
	v_lshlrev_b32_e32 v176, 16, v210
	v_and_b32_e32 v177, s19, v210
	v_lshlrev_b32_e32 v178, 16, v211
	v_and_b32_e32 v179, s19, v211
	v_lshlrev_b32_e32 v182, 16, v212
	v_and_b32_e32 v183, s19, v212
	v_lshlrev_b32_e32 v184, 16, v213
	v_and_b32_e32 v185, s19, v213
	v_pk_mul_f32 v[28:29], v[28:29], v[176:177]
	v_pk_mul_f32 v[30:31], v[30:31], v[178:179]
	v_pk_mul_f32 v[24:25], v[24:25], v[182:183]
	v_pk_mul_f32 v[26:27], v[26:27], v[184:185]
	v_add_u32_e32 v180, 0x50000, v181
	global_load_dwordx4 v[210:213], v180, s[64:65]
	s_waitcnt vmcnt(15)
	v_lshlrev_b32_e32 v176, 16, v214
	v_and_b32_e32 v177, s19, v214
	v_lshlrev_b32_e32 v178, 16, v215
	v_and_b32_e32 v179, s19, v215
	v_lshlrev_b32_e32 v182, 16, v216
	v_and_b32_e32 v183, s19, v216
	v_lshlrev_b32_e32 v184, 16, v217
	v_and_b32_e32 v185, s19, v217
	s_cbranch_execz .Ldry_epics_real
; __device__ __forceinline__ unsigned cvt_pk_bf16(float lo, float hi) { f32x2_t v = {lo, hi}; bf16x2_t b = __builtin_convertvector(v, bf16x2_t); return __builtin_bit_cast(unsigned, b); }
; __device__ __forceinline__ float bf2f(unsigned u) { return __uint_as_float(u << 16); }
;     __device__ __forceinline__ void operator()(const f32x4 (&acc)[2][2][4][2], const pg8::Unit& u, int wr, int wc, int fr, int fq) const {
;     ...
; #pragma unroll
;             for (int mm = 0; mm < 2; ++mm)
; #pragma unroll
;                 for (int bj = 0; bj < 2; ++bj) {
;                     const int m = 2 * mh + mm;
;                     const size_t row = (size_t)(row0 + ai * 128 + m * 16); const int col = col0 + bj * 128;
;                     const u32x4 gt = gv[mm][bj];
;                     f32x4 a = acc[ai][bj][m][0], b = acc[ai][bj][m][1];
;                     a[0] *= bf2f(gt.x & 0xffffu); a[1] *= bf2f(gt.x >> 16); a[2] *= bf2f(gt.y & 0xffffu); a[3] *= bf2f(gt.y >> 16);
;                     b[0] *= bf2f(gt.z & 0xffffu); b[1] *= bf2f(gt.z >> 16); b[2] *= bf2f(gt.w & 0xffffu); b[3] *= bf2f(gt.w >> 16);
;                     if (!second) { u32x4 w; w.x = cvt_pk_bf16(a[0], a[1]); w.y = cvt_pk_bf16(a[2], a[3]); w.z = cvt_pk_bf16(b[0], b[1]); w.w = cvt_pk_bf16(b[2], b[3]); *(u32x4*)((bf16_t*)tmp + row * 1024 + col) = w; }
;                     else {
;                         { const u32x4 t = tv[mm][bj]; a[0] += bf2f(t.x & 0xffffu); a[1] += bf2f(t.x >> 16); a[2] += bf2f(t.y & 0xffffu); a[3] += bf2f(t.y >> 16);
;                           b[0] += bf2f(t.z & 0xffffu); b[1] += bf2f(t.z >> 16); b[2] += bf2f(t.w & 0xffffu); b[3] += bf2f(t.w >> 16); }
;                         u32x4 w; w.x = cvt_pk_bf16(a[0], a[1]); w.y = cvt_pk_bf16(a[2], a[3]); w.z = cvt_pk_bf16(b[0], b[1]); w.w = cvt_pk_bf16(b[2], b[3]);
;                         *(u32x4*)(Y + row * 1024 + col) = w;
;                     }
.Ldry_epics_c3:
	v_pk_mul_f32 v[20:21], v[20:21], v[176:177]
	v_pk_mul_f32 v[22:23], v[22:23], v[178:179]
	v_pk_mul_f32 v[16:17], v[16:17], v[182:183]
	v_pk_mul_f32 v[18:19], v[18:19], v[184:185]
	global_load_dwordx4 v[214:217], v180, s[64:65] offset:256
	s_waitcnt vmcnt(15)
	v_lshlrev_b32_e32 v176, 16, v218
	v_and_b32_e32 v177, s19, v218
	v_lshlrev_b32_e32 v178, 16, v219
	v_and_b32_e32 v179, s19, v219
	v_lshlrev_b32_e32 v182, 16, v220
	v_and_b32_e32 v183, s19, v220
	v_lshlrev_b32_e32 v184, 16, v221
	v_and_b32_e32 v185, s19, v221
	v_pk_mul_f32 v[12:13], v[12:13], v[176:177]
	v_pk_mul_f32 v[14:15], v[14:15], v[178:179]
	v_pk_mul_f32 v[8:9], v[8:9], v[182:183]
	v_pk_mul_f32 v[10:11], v[10:11], v[184:185]
	v_add_u32_e32 v180, 0x58000, v181
	global_load_dwordx4 v[218:221], v180, s[64:65]
	s_waitcnt vmcnt(15)
	v_lshlrev_b32_e32 v176, 16, v222
	v_and_b32_e32 v177, s19, v222
	v_lshlrev_b32_e32 v178, 16, v223
	v_and_b32_e32 v179, s19, v223
	v_lshlrev_b32_e32 v182, 16, v224
	v_and_b32_e32 v183, s19, v224
	v_lshlrev_b32_e32 v184, 16, v225
	v_and_b32_e32 v185, s19, v225
	v_pk_mul_f32 v[4:5], v[4:5], v[176:177]
	v_pk_mul_f32 v[6:7], v[6:7], v[178:179]
	v_pk_mul_f32 v[0:1], v[0:1], v[182:183]
	v_pk_mul_f32 v[2:3], v[2:3], v[184:185]
	global_load_dwordx4 v[222:225], v180, s[64:65] offset:256
	s_waitcnt vmcnt(15)
	v_lshlrev_b32_e32 v176, 16, v72
	v_and_b32_e32 v177, s19, v72
	v_lshlrev_b32_e32 v178, 16, v73
	v_and_b32_e32 v179, s19, v73
	v_lshlrev_b32_e32 v182, 16, v74
	v_and_b32_e32 v183, s19, v74
	v_lshlrev_b32_e32 v184, 16, v75
	v_and_b32_e32 v185, s19, v75
	v_pk_add_f32 v[140:141], v[140:141], v[176:177]
	v_pk_add_f32 v[142:143], v[142:143], v[178:179]
	v_pk_add_f32 v[136:137], v[136:137], v[182:183]
	v_pk_add_f32 v[138:139], v[138:139], v[184:185]
	v_cvt_pk_bf16_f32 v140, v140, v141
	v_cvt_pk_bf16_f32 v141, v142, v143
	v_cvt_pk_bf16_f32 v142, v136, v137
	v_cvt_pk_bf16_f32 v143, v138, v139
	v_mov_b32_e32 v180, v181
	global_store_dwordx4 v180, v[140:143], s[42:43]
	s_waitcnt vmcnt(15)
	v_lshlrev_b32_e32 v176, 16, v84
	v_and_b32_e32 v177, s19, v84
	v_lshlrev_b32_e32 v178, 16, v85
	v_and_b32_e32 v179, s19, v85
	v_lshlrev_b32_e32 v182, 16, v86
	v_and_b32_e32 v183, s19, v86
	v_lshlrev_b32_e32 v184, 16, v87
	v_and_b32_e32 v185, s19, v87
	v_pk_add_f32 v[132:133], v[132:133], v[176:177]
	v_pk_add_f32 v[134:135], v[134:135], v[178:179]
	v_pk_add_f32 v[128:129], v[128:129], v[182:183]
	v_pk_add_f32 v[130:131], v[130:131], v[184:185]
	s_cbranch_execz .Ldry_epics_real
.Ldry_epics_c4:
	v_cvt_pk_bf16_f32 v132, v132, v133
	v_cvt_pk_bf16_f32 v133, v134, v135
	v_cvt_pk_bf16_f32 v134, v128, v129
	v_cvt_pk_bf16_f32 v135, v130, v131
	global_store_dwordx4 v180, v[132:135], s[42:43] offset:256
	s_waitcnt vmcnt(15)
	v_lshlrev_b32_e32 v176, 16, v96
	v_and_b32_e32 v177, s19, v96
	v_lshlrev_b32_e32 v178, 16, v97
	v_and_b32_e32 v179, s19, v97
	v_lshlrev_b32_e32 v182, 16, v98
	v_and_b32_e32 v183, s19, v98
	v_lshlrev_b32_e32 v184, 16, v99
	v_and_b32_e32 v185, s19, v99
	v_pk_add_f32 v[124:125], v[124:125], v[176:177]
	v_pk_add_f32 v[126:127], v[126:127], v[178:179]
	v_pk_add_f32 v[120:121], v[120:121], v[182:183]
	v_pk_add_f32 v[122:123], v[122:123], v[184:185]
	v_cvt_pk_bf16_f32 v124, v124, v125
	v_cvt_pk_bf16_f32 v125, v126, v127
	v_cvt_pk_bf16_f32 v126, v120, v121
	v_cvt_pk_bf16_f32 v127, v122, v123
	v_add_u32_e32 v180, 0x8000, v181
	global_store_dwordx4 v180, v[124:127], s[42:43]
	s_waitcnt vmcnt(15)
	v_lshlrev_b32_e32 v176, 16, v100
	v_and_b32_e32 v177, s19, v100
	v_lshlrev_b32_e32 v178, 16, v101
	v_and_b32_e32 v179, s19, v101
	v_lshlrev_b32_e32 v182, 16, v102
	v_and_b32_e32 v183, s19, v102
	v_lshlrev_b32_e32 v184, 16, v103
	v_and_b32_e32 v185, s19, v103
	v_pk_add_f32 v[116:117], v[116:117], v[176:177]
	v_pk_add_f32 v[118:119], v[118:119], v[178:179]
	v_pk_add_f32 v[112:113], v[112:113], v[182:183]
	v_pk_add_f32 v[114:115], v[114:115], v[184:185]
	v_cvt_pk_bf16_f32 v116, v116, v117
	v_cvt_pk_bf16_f32 v117, v118, v119
	v_cvt_pk_bf16_f32 v118, v112, v113
	v_cvt_pk_bf16_f32 v119, v114, v115
	global_store_dwordx4 v180, v[116:119], s[42:43] offset:256
	s_waitcnt vmcnt(15)
	v_lshlrev_b32_e32 v176, 16, v144
	v_and_b32_e32 v177, s19, v144
	v_lshlrev_b32_e32 v178, 16, v145
	v_and_b32_e32 v179, s19, v145
	v_lshlrev_b32_e32 v182, 16, v146
	v_and_b32_e32 v183, s19, v146
	v_lshlrev_b32_e32 v184, 16, v147
	v_and_b32_e32 v185, s19, v147
	v_pk_add_f32 v[108:109], v[108:109], v[176:177]
	v_pk_add_f32 v[110:111], v[110:111], v[178:179]
	v_pk_add_f32 v[104:105], v[104:105], v[182:183]
	v_pk_add_f32 v[106:107], v[106:107], v[184:185]
	v_cvt_pk_bf16_f32 v108, v108, v109
	v_cvt_pk_bf16_f32 v109, v110, v111
	v_cvt_pk_bf16_f32 v110, v104, v105
	v_cvt_pk_bf16_f32 v111, v106, v107
	v_add_u32_e32 v180, 0x10000, v181
	global_store_dwordx4 v180, v[108:111], s[42:43]
	s_waitcnt vmcnt(15)
	v_lshlrev_b32_e32 v176, 16, v148
	v_and_b32_e32 v177, s19, v148
	v_lshlrev_b32_e32 v178, 16, v149
	v_and_b32_e32 v179, s19, v149
	s_cbranch_execz .Ldry_epics_real
; __device__ __forceinline__ unsigned cvt_pk_bf16(float lo, float hi) { f32x2_t v = {lo, hi}; bf16x2_t b = __builtin_convertvector(v, bf16x2_t); return __builtin_bit_cast(unsigned, b); }
; __device__ __forceinline__ float bf2f(unsigned u) { return __uint_as_float(u << 16); }
;     __device__ __forceinline__ void operator()(const f32x4 (&acc)[2][2][4][2], const pg8::Unit& u, int wr, int wc, int fr, int fq) const {
;     ...
;                     else {
;                         { const u32x4 t = tv[mm][bj]; a[0] += bf2f(t.x & 0xffffu); a[1] += bf2f(t.x >> 16); a[2] += bf2f(t.y & 0xffffu); a[3] += bf2f(t.y >> 16);
;                           b[0] += bf2f(t.z & 0xffffu); b[1] += bf2f(t.z >> 16); b[2] += bf2f(t.w & 0xffffu); b[3] += bf2f(t.w >> 16); }
;                         u32x4 w; w.x = cvt_pk_bf16(a[0], a[1]); w.y = cvt_pk_bf16(a[2], a[3]); w.z = cvt_pk_bf16(b[0], b[1]); w.w = cvt_pk_bf16(b[2], b[3]);
;                         *(u32x4*)(Y + row * 1024 + col) = w;
;                     }
.Ldry_epics_c5:
	v_lshlrev_b32_e32 v182, 16, v150
	v_and_b32_e32 v183, s19, v150
	v_lshlrev_b32_e32 v184, 16, v151
	v_and_b32_e32 v185, s19, v151
	v_pk_add_f32 v[92:93], v[92:93], v[176:177]
	v_pk_add_f32 v[94:95], v[94:95], v[178:179]
	v_pk_add_f32 v[88:89], v[88:89], v[182:183]
	v_pk_add_f32 v[90:91], v[90:91], v[184:185]
	v_cvt_pk_bf16_f32 v92, v92, v93
	v_cvt_pk_bf16_f32 v93, v94, v95
	v_cvt_pk_bf16_f32 v94, v88, v89
	v_cvt_pk_bf16_f32 v95, v90, v91
	global_store_dwordx4 v180, v[92:95], s[42:43] offset:256
	s_waitcnt vmcnt(15)
	v_lshlrev_b32_e32 v176, 16, v152
	v_and_b32_e32 v177, s19, v152
	v_lshlrev_b32_e32 v178, 16, v153
	v_and_b32_e32 v179, s19, v153
	v_lshlrev_b32_e32 v182, 16, v154
	v_and_b32_e32 v183, s19, v154
	v_lshlrev_b32_e32 v184, 16, v155
	v_and_b32_e32 v185, s19, v155
	v_pk_add_f32 v[80:81], v[80:81], v[176:177]
	v_pk_add_f32 v[82:83], v[82:83], v[178:179]
	v_pk_add_f32 v[76:77], v[76:77], v[182:183]
	v_pk_add_f32 v[78:79], v[78:79], v[184:185]
	v_cvt_pk_bf16_f32 v80, v80, v81
	v_cvt_pk_bf16_f32 v81, v82, v83
	v_cvt_pk_bf16_f32 v82, v76, v77
	v_cvt_pk_bf16_f32 v83, v78, v79
	v_add_u32_e32 v180, 0x18000, v181
	global_store_dwordx4 v180, v[80:83], s[42:43]
	s_waitcnt vmcnt(15)
	v_lshlrev_b32_e32 v176, 16, v156
	v_and_b32_e32 v177, s19, v156
	v_lshlrev_b32_e32 v178, 16, v157
	v_and_b32_e32 v179, s19, v157
	v_lshlrev_b32_e32 v182, 16, v158
	v_and_b32_e32 v183, s19, v158
	v_lshlrev_b32_e32 v184, 16, v159
	v_and_b32_e32 v185, s19, v159
	v_pk_add_f32 v[68:69], v[68:69], v[176:177]
	v_pk_add_f32 v[70:71], v[70:71], v[178:179]
	v_pk_add_f32 v[64:65], v[64:65], v[182:183]
	v_pk_add_f32 v[66:67], v[66:67], v[184:185]
	v_cvt_pk_bf16_f32 v68, v68, v69
	v_cvt_pk_bf16_f32 v69, v70, v71
	v_cvt_pk_bf16_f32 v70, v64, v65
	v_cvt_pk_bf16_f32 v71, v66, v67
	global_store_dwordx4 v180, v[68:71], s[42:43] offset:256
	s_waitcnt vmcnt(15)
	v_lshlrev_b32_e32 v176, 16, v192
	v_and_b32_e32 v177, s19, v192
	v_lshlrev_b32_e32 v178, 16, v193
	v_and_b32_e32 v179, s19, v193
	v_lshlrev_b32_e32 v182, 16, v194
	v_and_b32_e32 v183, s19, v194
	v_lshlrev_b32_e32 v184, 16, v195
	v_and_b32_e32 v185, s19, v195
	v_pk_add_f32 v[60:61], v[60:61], v[176:177]
	v_pk_add_f32 v[62:63], v[62:63], v[178:179]
	v_pk_add_f32 v[56:57], v[56:57], v[182:183]
	v_pk_add_f32 v[58:59], v[58:59], v[184:185]
	v_cvt_pk_bf16_f32 v60, v60, v61
	v_cvt_pk_bf16_f32 v61, v62, v63
	v_cvt_pk_bf16_f32 v62, v56, v57
	s_cbranch_execz .Ldry_epics_real
.Ldry_epics_c6:
	v_cvt_pk_bf16_f32 v63, v58, v59
	v_add_u32_e32 v180, 0x40000, v181
	global_store_dwordx4 v180, v[60:63], s[42:43]
	s_waitcnt vmcnt(15)
	v_lshlrev_b32_e32 v176, 16, v196
	v_and_b32_e32 v177, s19, v196
	v_lshlrev_b32_e32 v178, 16, v197
	v_and_b32_e32 v179, s19, v197
	v_lshlrev_b32_e32 v182, 16, v198
	v_and_b32_e32 v183, s19, v198
	v_lshlrev_b32_e32 v184, 16, v199
	v_and_b32_e32 v185, s19, v199
	v_pk_add_f32 v[52:53], v[52:53], v[176:177]
	v_pk_add_f32 v[54:55], v[54:55], v[178:179]
	v_pk_add_f32 v[48:49], v[48:49], v[182:183]
	v_pk_add_f32 v[50:51], v[50:51], v[184:185]
	v_cvt_pk_bf16_f32 v52, v52, v53
	v_cvt_pk_bf16_f32 v53, v54, v55
	v_cvt_pk_bf16_f32 v54, v48, v49
	v_cvt_pk_bf16_f32 v55, v50, v51
	global_store_dwordx4 v180, v[52:55], s[42:43] offset:256
	s_waitcnt vmcnt(15)
	v_lshlrev_b32_e32 v176, 16, v202
	v_and_b32_e32 v177, s19, v202
	v_lshlrev_b32_e32 v178, 16, v203
	v_and_b32_e32 v179, s19, v203
	v_lshlrev_b32_e32 v182, 16, v204
	v_and_b32_e32 v183, s19, v204
	v_lshlrev_b32_e32 v184, 16, v205
	v_and_b32_e32 v185, s19, v205
	v_pk_add_f32 v[44:45], v[44:45], v[176:177]
	v_pk_add_f32 v[46:47], v[46:47], v[178:179]
	v_pk_add_f32 v[40:41], v[40:41], v[182:183]
	v_pk_add_f32 v[42:43], v[42:43], v[184:185]
	v_cvt_pk_bf16_f32 v44, v44, v45
	v_cvt_pk_bf16_f32 v45, v46, v47
	v_cvt_pk_bf16_f32 v46, v40, v41
	v_cvt_pk_bf16_f32 v47, v42, v43
	v_add_u32_e32 v180, 0x48000, v181
	global_store_dwordx4 v180, v[44:47], s[42:43]
	s_waitcnt vmcnt(15)
	v_lshlrev_b32_e32 v176, 16, v206
	v_and_b32_e32 v177, s19, v206
	v_lshlrev_b32_e32 v178, 16, v207
	v_and_b32_e32 v179, s19, v207
	v_lshlrev_b32_e32 v182, 16, v208
	v_and_b32_e32 v183, s19, v208
	v_lshlrev_b32_e32 v184, 16, v209
	v_and_b32_e32 v185, s19, v209
	v_pk_add_f32 v[36:37], v[36:37], v[176:177]
	v_pk_add_f32 v[38:39], v[38:39], v[178:179]
	v_pk_add_f32 v[32:33], v[32:33], v[182:183]
	v_pk_add_f32 v[34:35], v[34:35], v[184:185]
	v_cvt_pk_bf16_f32 v36, v36, v37
	v_cvt_pk_bf16_f32 v37, v38, v39
	v_cvt_pk_bf16_f32 v38, v32, v33
	v_cvt_pk_bf16_f32 v39, v34, v35
	global_store_dwordx4 v180, v[36:39], s[42:43] offset:256
	s_waitcnt vmcnt(15)
	v_lshlrev_b32_e32 v176, 16, v210
	v_and_b32_e32 v177, s19, v210
	v_lshlrev_b32_e32 v178, 16, v211
	v_and_b32_e32 v179, s19, v211
	v_lshlrev_b32_e32 v182, 16, v212
	v_and_b32_e32 v183, s19, v212
	v_lshlrev_b32_e32 v184, 16, v213
	s_cbranch_execz .Ldry_epics_real
; __device__ __forceinline__ unsigned cvt_pk_bf16(float lo, float hi) { f32x2_t v = {lo, hi}; bf16x2_t b = __builtin_convertvector(v, bf16x2_t); return __builtin_bit_cast(unsigned, b); }
; #define PG8_BAR __builtin_amdgcn_s_barrier()
; __device__ __forceinline__ float bf2f(unsigned u) { return __uint_as_float(u << 16); }
; template <class Epi, class Sched, bool ALIGN_EPI = false, bool SP2 = false>
; __device__ __forceinline__ void gemm_phase(LAS unsigned char* lds, const Gemm g, const Sched& S, const Epi& E) {
;     ...
;         if constexpr (!Epi::AFTER_DRAIN) { E(acc, cur, wr, wc, fr, fq); S.done(cur); }
;         if (!has_next) break;
; #pragma unroll
;         for (int a = 0; a < 2; ++a)
; #pragma unroll
;             for (int b = 0; b < 2; ++b)
; #pragma unroll
;                 for (int m = 0; m < 4; ++m)
; #pragma unroll
;                     for (int n = 0; n < 2; ++n) acc[a][b][m][n] = (f32x4){0.f, 0.f, 0.f, 0.f};
;         cur = nxt; cA = nA; cB = nB; ++ui;
;         if constexpr (ALIGN_EPI) { if (wr == 1) PG8_BAR; }
;     __device__ __forceinline__ void operator()(const f32x4 (&acc)[2][2][4][2], const pg8::Unit& u, int wr, int wc, int fr, int fq) const {
;     ...
;                     else {
;                         { const u32x4 t = tv[mm][bj]; a[0] += bf2f(t.x & 0xffffu); a[1] += bf2f(t.x >> 16); a[2] += bf2f(t.y & 0xffffu); a[3] += bf2f(t.y >> 16);
;                           b[0] += bf2f(t.z & 0xffffu); b[1] += bf2f(t.z >> 16); b[2] += bf2f(t.w & 0xffffu); b[3] += bf2f(t.w >> 16); }
;                         u32x4 w; w.x = cvt_pk_bf16(a[0], a[1]); w.y = cvt_pk_bf16(a[2], a[3]); w.z = cvt_pk_bf16(b[0], b[1]); w.w = cvt_pk_bf16(b[2], b[3]);
;                         *(u32x4*)(Y + row * 1024 + col) = w;
;                     }
.Ldry_epics_c7:
	v_and_b32_e32 v185, s19, v213
	v_pk_add_f32 v[28:29], v[28:29], v[176:177]
	v_pk_add_f32 v[30:31], v[30:31], v[178:179]
	v_pk_add_f32 v[24:25], v[24:25], v[182:183]
	v_pk_add_f32 v[26:27], v[26:27], v[184:185]
	v_cvt_pk_bf16_f32 v28, v28, v29
	v_cvt_pk_bf16_f32 v29, v30, v31
	v_cvt_pk_bf16_f32 v30, v24, v25
	v_cvt_pk_bf16_f32 v31, v26, v27
	v_add_u32_e32 v180, 0x50000, v181
	global_store_dwordx4 v180, v[28:31], s[42:43]
	s_waitcnt vmcnt(15)
	v_lshlrev_b32_e32 v176, 16, v214
	v_and_b32_e32 v177, s19, v214
	v_lshlrev_b32_e32 v178, 16, v215
	v_and_b32_e32 v179, s19, v215
	v_lshlrev_b32_e32 v182, 16, v216
	v_and_b32_e32 v183, s19, v216
	v_lshlrev_b32_e32 v184, 16, v217
	v_and_b32_e32 v185, s19, v217
	v_pk_add_f32 v[20:21], v[20:21], v[176:177]
	v_pk_add_f32 v[22:23], v[22:23], v[178:179]
	v_pk_add_f32 v[16:17], v[16:17], v[182:183]
	v_pk_add_f32 v[18:19], v[18:19], v[184:185]
	v_cvt_pk_bf16_f32 v20, v20, v21
	v_cvt_pk_bf16_f32 v21, v22, v23
	v_cvt_pk_bf16_f32 v22, v16, v17
	v_cvt_pk_bf16_f32 v23, v18, v19
	global_store_dwordx4 v180, v[20:23], s[42:43] offset:256
	s_waitcnt vmcnt(15)
	v_lshlrev_b32_e32 v176, 16, v218
	v_and_b32_e32 v177, s19, v218
	v_lshlrev_b32_e32 v178, 16, v219
	v_and_b32_e32 v179, s19, v219
	v_lshlrev_b32_e32 v182, 16, v220
	v_and_b32_e32 v183, s19, v220
	v_lshlrev_b32_e32 v184, 16, v221
	v_and_b32_e32 v185, s19, v221
	v_pk_add_f32 v[12:13], v[12:13], v[176:177]
	v_pk_add_f32 v[14:15], v[14:15], v[178:179]
	v_pk_add_f32 v[8:9], v[8:9], v[182:183]
	v_pk_add_f32 v[10:11], v[10:11], v[184:185]
	v_cvt_pk_bf16_f32 v12, v12, v13
	v_cvt_pk_bf16_f32 v13, v14, v15
	v_cvt_pk_bf16_f32 v14, v8, v9
	v_cvt_pk_bf16_f32 v15, v10, v11
	v_add_u32_e32 v180, 0x58000, v181
	global_store_dwordx4 v180, v[12:15], s[42:43]
	s_waitcnt vmcnt(15)
	v_lshlrev_b32_e32 v176, 16, v222
	v_and_b32_e32 v177, s19, v222
	v_lshlrev_b32_e32 v178, 16, v223
	v_and_b32_e32 v179, s19, v223
	v_lshlrev_b32_e32 v182, 16, v224
	v_and_b32_e32 v183, s19, v224
	v_lshlrev_b32_e32 v184, 16, v225
	v_and_b32_e32 v185, s19, v225
	v_pk_add_f32 v[4:5], v[4:5], v[176:177]
	v_pk_add_f32 v[6:7], v[6:7], v[178:179]
	v_pk_add_f32 v[0:1], v[0:1], v[182:183]
	v_pk_add_f32 v[2:3], v[2:3], v[184:185]
	v_cvt_pk_bf16_f32 v4, v4, v5
	v_cvt_pk_bf16_f32 v5, v6, v7
	v_cvt_pk_bf16_f32 v6, v0, v1
	v_cvt_pk_bf16_f32 v7, v2, v3
	global_store_dwordx4 v180, v[4:7], s[42:43] offset:256
	s_cbranch_execz .Ldry_epics_real
.Lepic_done:
	s_andn2_b64 vcc, exec, s[6:7]
	s_mov_b64 s[4:5], -1
	s_cbranch_vccnz .LBB0_601
	s_andn2_b64 vcc, exec, s[10:11]
	s_cbranch_vccnz .LBB0_600
	s_barrier
	s_branch .LBB0_600
